# scan: two rows per lane held in swapped roles on odd lanes so one merged 16-lane DPP reduction (5 ops) serves both rows; off-chain work fills the DPP gaps
# baseline (speedup 1.0000x reference)
; #define LAS __attribute__((address_space(3)))
; __device__ __forceinline__ void scan_unit(const Args& A, LAS unsigned char* lds, int s, int tid) {
;     ...
;             const LAS float* st = cur + 4 * jq; const LAS float* vp = cur + SC_V_OFF + rl;
;             f32x4 a = *(const LAS f32x4*)(st), bb = *(const LAS f32x4*)(st + 64), k = *(const LAS f32x4*)(st + 128), r = *(const LAS f32x4*)(st + 192);
;             float v = vp[0];
;             f32x4 a1 = *(const LAS f32x4*)(st + SC_STEP_F), bb1 = *(const LAS f32x4*)(st + SC_STEP_F + 64), k1 = *(const LAS f32x4*)(st + SC_STEP_F + 128), r1 = *(const LAS f32x4*)(st + SC_STEP_F + 192);
;             float v1 = vp[32];
;             f32x4 pr = (f32x4){0.f, 0.f, 0.f, 0.f};
; #pragma unroll
;             for (int tl = 0; tl < SC_TC; ++tl) {
;                 float sa, yy;
;                 asm volatile(
;                     "v_mul_f32_e32 %0, %2, %6\n\t"
;                     "v_mul_f32_e32 %1, %2, %10\n\t"
;                     "v_fmac_f32_e32 %0, %3, %7\n\t"
;                     "v_fmac_f32_e32 %1, %3, %11\n\t"
;                     "v_fmac_f32_e32 %0, %4, %8\n\t"
;                     "v_fmac_f32_e32 %1, %4, %12\n\t"
;                     "v_fmac_f32_e32 %0, %5, %9\n\t"
;                     "v_fmac_f32_e32 %1, %5, %13\n\t"
;                     "v_fmac_f32_e32 %2, %18, %14\n\t"
;                     "v_add_f32_dpp %0, %0, %0 quad_perm:[1,0,3,2] row_mask:0xf bank_mask:0xf\n\t"
;                     "v_fmac_f32_e32 %3, %18, %15\n\t"
;                     "v_fmac_f32_e32 %4, %18, %16\n\t"
;                     "v_add_f32_dpp %0, %0, %0 quad_perm:[2,3,0,1] row_mask:0xf bank_mask:0xf\n\t"
;                     "v_fmac_f32_e32 %5, %18, %17\n\t"
;                     "s_nop 0\n\t"
;                     "v_add_f32_dpp %0, %0, %0 row_half_mirror row_mask:0xf bank_mask:0xf\n\t"
;                     : "=&v"(sa), "=&v"(yy), "+v"(S0), "+v"(S1), "+v"(S2), "+v"(S3)
;                     : "v"(a.x), "v"(a.y), "v"(a.z), "v"(a.w), "v"(pr.x), "v"(pr.y), "v"(pr.z), "v"(pr.w), "v"(k.x), "v"(k.y), "v"(k.z), "v"(k.w), "v"(v));
;                 if (tl > 0) yb[(tl - 1) * SC_YS + lane] = yy;
;                 const f32x4 b_now = bb; pr = r;
;                 a = a1; bb = bb1; k = k1; r = r1; v = v1;
;                 if (tl + 2 < SC_TC) { const LAS float* sn = st + (tl + 2) * SC_STEP_F;
.LBB0_506:
	s_and_b32 s0, s9, 1
	s_cmp_eq_u32 s0, 0
	s_cselect_b64 s[6:7], -1, 0
	s_and_b64 s[0:1], s[6:7], exec
	s_cselect_b32 s0, 0, s8
	s_cselect_b32 s1, s38, s39
	v_add_u32_e32 v30, s0, v71
	s_cselect_b32 s0, s40, s42
	s_add_i32 s1, s1, s43
	v_lshl_add_u32 v31, v79, 2, s1
	s_cmp_gt_u32 s43, 63
	s_cbranch_scc1 .Lsc2_skip
	v_add_u32_e32 v31, s43, v31
	s_mul_i32 s1, s43, 0x220
	v_add_u32_e32 v204, s1, v81
	v_mbcnt_lo_u32_b32 v207, -1, 0
	v_mbcnt_hi_u32_b32 v207, -1, v207
	v_and_b32_e32 v207, 1, v207
	v_lshlrev_b32_e32 v208, 4, v207
	v_sub_u32_e32 v205, v31, v208
	v_add_u32_e32 v205, 16, v205
	v_add_u32_e32 v31, v31, v208
	v_mul_u32_u24_e32 v208, 0x2200, v207
	v_sub_u32_e32 v206, v204, v208
	v_add_u32_e32 v206, 0x2200, v206
	v_add_u32_e32 v204, v204, v208
	ds_read_b128 v[132:135], v30 offset:0
	ds_read_b128 v[136:139], v30 offset:256
	ds_read_b128 v[140:143], v30 offset:512
	ds_read_b128 v[144:147], v30 offset:768
	ds_read_b32 v148, v31 offset:0
	ds_read_b32 v149, v205 offset:0
	ds_read_b128 v[152:155], v30 offset:1024
	ds_read_b128 v[156:159], v30 offset:1280
	ds_read_b128 v[160:163], v30 offset:1536
	ds_read_b128 v[164:167], v30 offset:1792
	ds_read_b32 v168, v31 offset:128
	ds_read_b32 v169, v205 offset:128
	s_waitcnt lgkmcnt(11)
	v_pk_mul_f32 v[192:193], v[122:123], v[132:133]
	v_pk_mul_f32 v[194:195], v[126:127], v[132:133]
	v_pk_fma_f32 v[192:193], v[124:125], v[134:135], v[192:193]
	v_pk_fma_f32 v[194:195], v[128:129], v[134:135], v[194:195]
	v_add_f32_e32 v192, v192, v193
	v_add_f32_e32 v194, v194, v195
	s_waitcnt lgkmcnt(6)
	v_pk_fma_f32 v[122:123], v[148:149], v[140:141], v[122:123] op_sel_hi:[0,1,1]
	v_add_f32_dpp v192, v194, v192 quad_perm:[1,0,3,2] row_mask:0xf bank_mask:0xf
	v_pk_fma_f32 v[126:127], v[148:149], v[140:141], v[126:127] op_sel:[1,0,0] op_sel_hi:[1,1,1]
	v_pk_fma_f32 v[124:125], v[148:149], v[142:143], v[124:125] op_sel_hi:[0,1,1]
	v_add_f32_dpp v192, v192, v192 quad_perm:[2,3,0,1] row_mask:0xf bank_mask:0xf
	v_pk_fma_f32 v[128:129], v[148:149], v[142:143], v[128:129] op_sel:[1,0,0] op_sel_hi:[1,1,1]
	ds_read_b128 v[172:175], v30 offset:2048
	v_add_f32_dpp v192, v192, v192 row_ror:4 row_mask:0xf bank_mask:0xf
	ds_read_b128 v[176:179], v30 offset:2304
	ds_read_b128 v[180:183], v30 offset:2560
	v_add_f32_dpp v192, v192, v192 row_ror:8 row_mask:0xf bank_mask:0xf
	ds_read_b128 v[184:187], v30 offset:2816
	ds_read_b32 v188, v31 offset:256
	ds_read_b32 v189, v205 offset:256
	v_mov_b32_dpp v194, v192 quad_perm:[1,0,3,2] row_mask:0xf bank_mask:0xf
	v_pk_fma_f32 v[122:123], v[192:193], v[136:137], v[122:123] op_sel_hi:[0,1,1]
	v_pk_fma_f32 v[126:127], v[194:195], v[136:137], v[126:127] op_sel_hi:[0,1,1]
	v_pk_fma_f32 v[124:125], v[192:193], v[138:139], v[124:125] op_sel_hi:[0,1,1]
	v_pk_fma_f32 v[128:129], v[194:195], v[138:139], v[128:129] op_sel_hi:[0,1,1]
	s_waitcnt lgkmcnt(11)
	v_pk_mul_f32 v[192:193], v[122:123], v[152:153]
	v_pk_mul_f32 v[194:195], v[126:127], v[152:153]
	v_pk_fma_f32 v[192:193], v[124:125], v[154:155], v[192:193]
	v_pk_fma_f32 v[194:195], v[128:129], v[154:155], v[194:195]
	v_add_f32_e32 v192, v192, v193
	v_add_f32_e32 v194, v194, v195
	v_pk_mul_f32 v[196:197], v[122:123], v[144:145]
	v_pk_mul_f32 v[198:199], v[126:127], v[144:145]
	v_pk_fma_f32 v[196:197], v[124:125], v[146:147], v[196:197]
	v_add_f32_dpp v192, v194, v192 quad_perm:[1,0,3,2] row_mask:0xf bank_mask:0xf
	v_pk_fma_f32 v[198:199], v[128:129], v[146:147], v[198:199]
	v_add_f32_e32 v196, v196, v197
	v_add_f32_e32 v198, v198, v199
	v_add_f32_dpp v192, v192, v192 quad_perm:[2,3,0,1] row_mask:0xf bank_mask:0xf
	s_waitcnt lgkmcnt(6)
	v_pk_fma_f32 v[122:123], v[168:169], v[160:161], v[122:123] op_sel_hi:[0,1,1]
	v_pk_fma_f32 v[126:127], v[168:169], v[160:161], v[126:127] op_sel:[1,0,0] op_sel_hi:[1,1,1]
	v_add_f32_dpp v192, v192, v192 row_ror:4 row_mask:0xf bank_mask:0xf
	v_pk_fma_f32 v[124:125], v[168:169], v[162:163], v[124:125] op_sel_hi:[0,1,1]
	v_pk_fma_f32 v[128:129], v[168:169], v[162:163], v[128:129] op_sel:[1,0,0] op_sel_hi:[1,1,1]
	ds_write_b32 v204, v196 offset:0
	v_add_f32_dpp v192, v192, v192 row_ror:8 row_mask:0xf bank_mask:0xf
	ds_write_b32 v206, v198 offset:0
	ds_read_b128 v[132:135], v30 offset:3072
	ds_read_b128 v[136:139], v30 offset:3328
	ds_read_b128 v[140:143], v30 offset:3584
	ds_read_b128 v[144:147], v30 offset:3840
	ds_read_b32 v148, v31 offset:384
	ds_read_b32 v149, v205 offset:384
	v_mov_b32_dpp v194, v192 quad_perm:[1,0,3,2] row_mask:0xf bank_mask:0xf
	v_pk_fma_f32 v[122:123], v[192:193], v[156:157], v[122:123] op_sel_hi:[0,1,1]
	v_pk_fma_f32 v[126:127], v[194:195], v[156:157], v[126:127] op_sel_hi:[0,1,1]
	v_pk_fma_f32 v[124:125], v[192:193], v[158:159], v[124:125] op_sel_hi:[0,1,1]
	v_pk_fma_f32 v[128:129], v[194:195], v[158:159], v[128:129] op_sel_hi:[0,1,1]
	s_waitcnt lgkmcnt(13)
	v_pk_mul_f32 v[192:193], v[122:123], v[172:173]
	v_pk_mul_f32 v[194:195], v[126:127], v[172:173]
	v_pk_fma_f32 v[192:193], v[124:125], v[174:175], v[192:193]
	v_pk_fma_f32 v[194:195], v[128:129], v[174:175], v[194:195]
	v_add_f32_e32 v192, v192, v193
	v_add_f32_e32 v194, v194, v195
	v_pk_mul_f32 v[196:197], v[122:123], v[164:165]
	v_pk_mul_f32 v[198:199], v[126:127], v[164:165]
	v_pk_fma_f32 v[196:197], v[124:125], v[166:167], v[196:197]
	v_add_f32_dpp v192, v194, v192 quad_perm:[1,0,3,2] row_mask:0xf bank_mask:0xf
	v_pk_fma_f32 v[198:199], v[128:129], v[166:167], v[198:199]
	v_add_f32_e32 v196, v196, v197
	v_add_f32_e32 v198, v198, v199
	v_add_f32_dpp v192, v192, v192 quad_perm:[2,3,0,1] row_mask:0xf bank_mask:0xf
	s_waitcnt lgkmcnt(8)
; #define LAS __attribute__((address_space(3)))
; __device__ __forceinline__ void scan_unit(const Args& A, LAS unsigned char* lds, int s, int tid) {
;     ...
;             const LAS float* st = cur + 4 * jq; const LAS float* vp = cur + SC_V_OFF + rl;
;             f32x4 a = *(const LAS f32x4*)(st), bb = *(const LAS f32x4*)(st + 64), k = *(const LAS f32x4*)(st + 128), r = *(const LAS f32x4*)(st + 192);
;             float v = vp[0];
;             f32x4 a1 = *(const LAS f32x4*)(st + SC_STEP_F), bb1 = *(const LAS f32x4*)(st + SC_STEP_F + 64), k1 = *(const LAS f32x4*)(st + SC_STEP_F + 128), r1 = *(const LAS f32x4*)(st + SC_STEP_F + 192);
;             float v1 = vp[32];
;             f32x4 pr = (f32x4){0.f, 0.f, 0.f, 0.f};
; #pragma unroll
;             for (int tl = 0; tl < SC_TC; ++tl) {
;                 float sa, yy;
;                 asm volatile(
;                     "v_mul_f32_e32 %0, %2, %6\n\t"
;                     "v_mul_f32_e32 %1, %2, %10\n\t"
;                     "v_fmac_f32_e32 %0, %3, %7\n\t"
;                     "v_fmac_f32_e32 %1, %3, %11\n\t"
;                     "v_fmac_f32_e32 %0, %4, %8\n\t"
;                     "v_fmac_f32_e32 %1, %4, %12\n\t"
;                     "v_fmac_f32_e32 %0, %5, %9\n\t"
;                     "v_fmac_f32_e32 %1, %5, %13\n\t"
;                     "v_fmac_f32_e32 %2, %18, %14\n\t"
;                     "v_add_f32_dpp %0, %0, %0 quad_perm:[1,0,3,2] row_mask:0xf bank_mask:0xf\n\t"
;                     "v_fmac_f32_e32 %3, %18, %15\n\t"
;                     "v_fmac_f32_e32 %4, %18, %16\n\t"
;                     "v_add_f32_dpp %0, %0, %0 quad_perm:[2,3,0,1] row_mask:0xf bank_mask:0xf\n\t"
;                     "v_fmac_f32_e32 %5, %18, %17\n\t"
;                     "s_nop 0\n\t"
;                     "v_add_f32_dpp %0, %0, %0 row_half_mirror row_mask:0xf bank_mask:0xf\n\t"
;                     : "=&v"(sa), "=&v"(yy), "+v"(S0), "+v"(S1), "+v"(S2), "+v"(S3)
;                     : "v"(a.x), "v"(a.y), "v"(a.z), "v"(a.w), "v"(pr.x), "v"(pr.y), "v"(pr.z), "v"(pr.w), "v"(k.x), "v"(k.y), "v"(k.z), "v"(k.w), "v"(v));
;                 if (tl > 0) yb[(tl - 1) * SC_YS + lane] = yy;
;                 const f32x4 b_now = bb; pr = r;
;                 a = a1; bb = bb1; k = k1; r = r1; v = v1;
;                 if (tl + 2 < SC_TC) { const LAS float* sn = st + (tl + 2) * SC_STEP_F;
	v_pk_fma_f32 v[122:123], v[188:189], v[180:181], v[122:123] op_sel_hi:[0,1,1]
	v_pk_fma_f32 v[126:127], v[188:189], v[180:181], v[126:127] op_sel:[1,0,0] op_sel_hi:[1,1,1]
	v_add_f32_dpp v192, v192, v192 row_ror:4 row_mask:0xf bank_mask:0xf
	v_pk_fma_f32 v[124:125], v[188:189], v[182:183], v[124:125] op_sel_hi:[0,1,1]
	v_pk_fma_f32 v[128:129], v[188:189], v[182:183], v[128:129] op_sel:[1,0,0] op_sel_hi:[1,1,1]
	ds_write_b32 v204, v196 offset:272
	v_add_f32_dpp v192, v192, v192 row_ror:8 row_mask:0xf bank_mask:0xf
	ds_write_b32 v206, v198 offset:272
	ds_read_b128 v[152:155], v30 offset:4096
	ds_read_b128 v[156:159], v30 offset:4352
	ds_read_b128 v[160:163], v30 offset:4608
	ds_read_b128 v[164:167], v30 offset:4864
	ds_read_b32 v168, v31 offset:512
	ds_read_b32 v169, v205 offset:512
	v_mov_b32_dpp v194, v192 quad_perm:[1,0,3,2] row_mask:0xf bank_mask:0xf
	v_pk_fma_f32 v[122:123], v[192:193], v[176:177], v[122:123] op_sel_hi:[0,1,1]
	v_pk_fma_f32 v[126:127], v[194:195], v[176:177], v[126:127] op_sel_hi:[0,1,1]
	v_pk_fma_f32 v[124:125], v[192:193], v[178:179], v[124:125] op_sel_hi:[0,1,1]
	v_pk_fma_f32 v[128:129], v[194:195], v[178:179], v[128:129] op_sel_hi:[0,1,1]
	s_waitcnt lgkmcnt(13)
	v_pk_mul_f32 v[192:193], v[122:123], v[132:133]
	v_pk_mul_f32 v[194:195], v[126:127], v[132:133]
	v_pk_fma_f32 v[192:193], v[124:125], v[134:135], v[192:193]
	v_pk_fma_f32 v[194:195], v[128:129], v[134:135], v[194:195]
	v_add_f32_e32 v192, v192, v193
	v_add_f32_e32 v194, v194, v195
	v_pk_mul_f32 v[196:197], v[122:123], v[184:185]
	v_pk_mul_f32 v[198:199], v[126:127], v[184:185]
	v_pk_fma_f32 v[196:197], v[124:125], v[186:187], v[196:197]
	v_add_f32_dpp v192, v194, v192 quad_perm:[1,0,3,2] row_mask:0xf bank_mask:0xf
	v_pk_fma_f32 v[198:199], v[128:129], v[186:187], v[198:199]
	v_add_f32_e32 v196, v196, v197
	v_add_f32_e32 v198, v198, v199
	v_add_f32_dpp v192, v192, v192 quad_perm:[2,3,0,1] row_mask:0xf bank_mask:0xf
	s_waitcnt lgkmcnt(8)
	v_pk_fma_f32 v[122:123], v[148:149], v[140:141], v[122:123] op_sel_hi:[0,1,1]
	v_pk_fma_f32 v[126:127], v[148:149], v[140:141], v[126:127] op_sel:[1,0,0] op_sel_hi:[1,1,1]
	v_add_f32_dpp v192, v192, v192 row_ror:4 row_mask:0xf bank_mask:0xf
	v_pk_fma_f32 v[124:125], v[148:149], v[142:143], v[124:125] op_sel_hi:[0,1,1]
	v_pk_fma_f32 v[128:129], v[148:149], v[142:143], v[128:129] op_sel:[1,0,0] op_sel_hi:[1,1,1]
	ds_write_b32 v204, v196 offset:544
	v_add_f32_dpp v192, v192, v192 row_ror:8 row_mask:0xf bank_mask:0xf
	ds_write_b32 v206, v198 offset:544
	ds_read_b128 v[172:175], v30 offset:5120
	ds_read_b128 v[176:179], v30 offset:5376
	ds_read_b128 v[180:183], v30 offset:5632
	ds_read_b128 v[184:187], v30 offset:5888
	ds_read_b32 v188, v31 offset:640
	ds_read_b32 v189, v205 offset:640
	v_mov_b32_dpp v194, v192 quad_perm:[1,0,3,2] row_mask:0xf bank_mask:0xf
	v_pk_fma_f32 v[122:123], v[192:193], v[136:137], v[122:123] op_sel_hi:[0,1,1]
	v_pk_fma_f32 v[126:127], v[194:195], v[136:137], v[126:127] op_sel_hi:[0,1,1]
	v_pk_fma_f32 v[124:125], v[192:193], v[138:139], v[124:125] op_sel_hi:[0,1,1]
	v_pk_fma_f32 v[128:129], v[194:195], v[138:139], v[128:129] op_sel_hi:[0,1,1]
	s_waitcnt lgkmcnt(13)
	v_pk_mul_f32 v[192:193], v[122:123], v[152:153]
	v_pk_mul_f32 v[194:195], v[126:127], v[152:153]
	v_pk_fma_f32 v[192:193], v[124:125], v[154:155], v[192:193]
	v_pk_fma_f32 v[194:195], v[128:129], v[154:155], v[194:195]
	v_add_f32_e32 v192, v192, v193
	v_add_f32_e32 v194, v194, v195
	v_pk_mul_f32 v[196:197], v[122:123], v[144:145]
	v_pk_mul_f32 v[198:199], v[126:127], v[144:145]
	v_pk_fma_f32 v[196:197], v[124:125], v[146:147], v[196:197]
	v_add_f32_dpp v192, v194, v192 quad_perm:[1,0,3,2] row_mask:0xf bank_mask:0xf
	v_pk_fma_f32 v[198:199], v[128:129], v[146:147], v[198:199]
	v_add_f32_e32 v196, v196, v197
	v_add_f32_e32 v198, v198, v199
	v_add_f32_dpp v192, v192, v192 quad_perm:[2,3,0,1] row_mask:0xf bank_mask:0xf
	s_waitcnt lgkmcnt(8)
	v_pk_fma_f32 v[122:123], v[168:169], v[160:161], v[122:123] op_sel_hi:[0,1,1]
	v_pk_fma_f32 v[126:127], v[168:169], v[160:161], v[126:127] op_sel:[1,0,0] op_sel_hi:[1,1,1]
	v_add_f32_dpp v192, v192, v192 row_ror:4 row_mask:0xf bank_mask:0xf
	v_pk_fma_f32 v[124:125], v[168:169], v[162:163], v[124:125] op_sel_hi:[0,1,1]
	v_pk_fma_f32 v[128:129], v[168:169], v[162:163], v[128:129] op_sel:[1,0,0] op_sel_hi:[1,1,1]
	ds_write_b32 v204, v196 offset:816
	v_add_f32_dpp v192, v192, v192 row_ror:8 row_mask:0xf bank_mask:0xf
	ds_write_b32 v206, v198 offset:816
	ds_read_b128 v[132:135], v30 offset:6144
	ds_read_b128 v[136:139], v30 offset:6400
	ds_read_b128 v[140:143], v30 offset:6656
	ds_read_b128 v[144:147], v30 offset:6912
	ds_read_b32 v148, v31 offset:768
	ds_read_b32 v149, v205 offset:768
	v_mov_b32_dpp v194, v192 quad_perm:[1,0,3,2] row_mask:0xf bank_mask:0xf
	v_pk_fma_f32 v[122:123], v[192:193], v[156:157], v[122:123] op_sel_hi:[0,1,1]
	v_pk_fma_f32 v[126:127], v[194:195], v[156:157], v[126:127] op_sel_hi:[0,1,1]
	v_pk_fma_f32 v[124:125], v[192:193], v[158:159], v[124:125] op_sel_hi:[0,1,1]
	v_pk_fma_f32 v[128:129], v[194:195], v[158:159], v[128:129] op_sel_hi:[0,1,1]
	s_waitcnt lgkmcnt(13)
	v_pk_mul_f32 v[192:193], v[122:123], v[172:173]
	v_pk_mul_f32 v[194:195], v[126:127], v[172:173]
	v_pk_fma_f32 v[192:193], v[124:125], v[174:175], v[192:193]
	v_pk_fma_f32 v[194:195], v[128:129], v[174:175], v[194:195]
	v_add_f32_e32 v192, v192, v193
	v_add_f32_e32 v194, v194, v195
	v_pk_mul_f32 v[196:197], v[122:123], v[164:165]
	v_pk_mul_f32 v[198:199], v[126:127], v[164:165]
	v_pk_fma_f32 v[196:197], v[124:125], v[166:167], v[196:197]
	v_add_f32_dpp v192, v194, v192 quad_perm:[1,0,3,2] row_mask:0xf bank_mask:0xf
	v_pk_fma_f32 v[198:199], v[128:129], v[166:167], v[198:199]
	v_add_f32_e32 v196, v196, v197
	v_add_f32_e32 v198, v198, v199
	v_add_f32_dpp v192, v192, v192 quad_perm:[2,3,0,1] row_mask:0xf bank_mask:0xf
	s_waitcnt lgkmcnt(8)
; #define LAS __attribute__((address_space(3)))
; __device__ __forceinline__ void scan_unit(const Args& A, LAS unsigned char* lds, int s, int tid) {
;     ...
;             const LAS float* st = cur + 4 * jq; const LAS float* vp = cur + SC_V_OFF + rl;
;             f32x4 a = *(const LAS f32x4*)(st), bb = *(const LAS f32x4*)(st + 64), k = *(const LAS f32x4*)(st + 128), r = *(const LAS f32x4*)(st + 192);
;             float v = vp[0];
;             f32x4 a1 = *(const LAS f32x4*)(st + SC_STEP_F), bb1 = *(const LAS f32x4*)(st + SC_STEP_F + 64), k1 = *(const LAS f32x4*)(st + SC_STEP_F + 128), r1 = *(const LAS f32x4*)(st + SC_STEP_F + 192);
;             float v1 = vp[32];
;             f32x4 pr = (f32x4){0.f, 0.f, 0.f, 0.f};
; #pragma unroll
;             for (int tl = 0; tl < SC_TC; ++tl) {
;                 float sa, yy;
;                 asm volatile(
;                     "v_mul_f32_e32 %0, %2, %6\n\t"
;                     "v_mul_f32_e32 %1, %2, %10\n\t"
;                     "v_fmac_f32_e32 %0, %3, %7\n\t"
;                     "v_fmac_f32_e32 %1, %3, %11\n\t"
;                     "v_fmac_f32_e32 %0, %4, %8\n\t"
;                     "v_fmac_f32_e32 %1, %4, %12\n\t"
;                     "v_fmac_f32_e32 %0, %5, %9\n\t"
;                     "v_fmac_f32_e32 %1, %5, %13\n\t"
;                     "v_fmac_f32_e32 %2, %18, %14\n\t"
;                     "v_add_f32_dpp %0, %0, %0 quad_perm:[1,0,3,2] row_mask:0xf bank_mask:0xf\n\t"
;                     "v_fmac_f32_e32 %3, %18, %15\n\t"
;                     "v_fmac_f32_e32 %4, %18, %16\n\t"
;                     "v_add_f32_dpp %0, %0, %0 quad_perm:[2,3,0,1] row_mask:0xf bank_mask:0xf\n\t"
;                     "v_fmac_f32_e32 %5, %18, %17\n\t"
;                     "s_nop 0\n\t"
;                     "v_add_f32_dpp %0, %0, %0 row_half_mirror row_mask:0xf bank_mask:0xf\n\t"
;                     : "=&v"(sa), "=&v"(yy), "+v"(S0), "+v"(S1), "+v"(S2), "+v"(S3)
;                     : "v"(a.x), "v"(a.y), "v"(a.z), "v"(a.w), "v"(pr.x), "v"(pr.y), "v"(pr.z), "v"(pr.w), "v"(k.x), "v"(k.y), "v"(k.z), "v"(k.w), "v"(v));
;                 if (tl > 0) yb[(tl - 1) * SC_YS + lane] = yy;
;                 const f32x4 b_now = bb; pr = r;
;                 a = a1; bb = bb1; k = k1; r = r1; v = v1;
;                 if (tl + 2 < SC_TC) { const LAS float* sn = st + (tl + 2) * SC_STEP_F;
	v_pk_fma_f32 v[122:123], v[188:189], v[180:181], v[122:123] op_sel_hi:[0,1,1]
	v_pk_fma_f32 v[126:127], v[188:189], v[180:181], v[126:127] op_sel:[1,0,0] op_sel_hi:[1,1,1]
	v_add_f32_dpp v192, v192, v192 row_ror:4 row_mask:0xf bank_mask:0xf
	v_pk_fma_f32 v[124:125], v[188:189], v[182:183], v[124:125] op_sel_hi:[0,1,1]
	v_pk_fma_f32 v[128:129], v[188:189], v[182:183], v[128:129] op_sel:[1,0,0] op_sel_hi:[1,1,1]
	ds_write_b32 v204, v196 offset:1088
	v_add_f32_dpp v192, v192, v192 row_ror:8 row_mask:0xf bank_mask:0xf
	ds_write_b32 v206, v198 offset:1088
	ds_read_b128 v[152:155], v30 offset:7168
	ds_read_b128 v[156:159], v30 offset:7424
	ds_read_b128 v[160:163], v30 offset:7680
	ds_read_b128 v[164:167], v30 offset:7936
	ds_read_b32 v168, v31 offset:896
	ds_read_b32 v169, v205 offset:896
	v_mov_b32_dpp v194, v192 quad_perm:[1,0,3,2] row_mask:0xf bank_mask:0xf
	v_pk_fma_f32 v[122:123], v[192:193], v[176:177], v[122:123] op_sel_hi:[0,1,1]
	v_pk_fma_f32 v[126:127], v[194:195], v[176:177], v[126:127] op_sel_hi:[0,1,1]
	v_pk_fma_f32 v[124:125], v[192:193], v[178:179], v[124:125] op_sel_hi:[0,1,1]
	v_pk_fma_f32 v[128:129], v[194:195], v[178:179], v[128:129] op_sel_hi:[0,1,1]
	s_waitcnt lgkmcnt(13)
	v_pk_mul_f32 v[192:193], v[122:123], v[132:133]
	v_pk_mul_f32 v[194:195], v[126:127], v[132:133]
	v_pk_fma_f32 v[192:193], v[124:125], v[134:135], v[192:193]
	v_pk_fma_f32 v[194:195], v[128:129], v[134:135], v[194:195]
	v_add_f32_e32 v192, v192, v193
	v_add_f32_e32 v194, v194, v195
	v_pk_mul_f32 v[196:197], v[122:123], v[184:185]
	v_pk_mul_f32 v[198:199], v[126:127], v[184:185]
	v_pk_fma_f32 v[196:197], v[124:125], v[186:187], v[196:197]
	v_add_f32_dpp v192, v194, v192 quad_perm:[1,0,3,2] row_mask:0xf bank_mask:0xf
	v_pk_fma_f32 v[198:199], v[128:129], v[186:187], v[198:199]
	v_add_f32_e32 v196, v196, v197
	v_add_f32_e32 v198, v198, v199
	v_add_f32_dpp v192, v192, v192 quad_perm:[2,3,0,1] row_mask:0xf bank_mask:0xf
	s_waitcnt lgkmcnt(8)
	v_pk_fma_f32 v[122:123], v[148:149], v[140:141], v[122:123] op_sel_hi:[0,1,1]
	v_pk_fma_f32 v[126:127], v[148:149], v[140:141], v[126:127] op_sel:[1,0,0] op_sel_hi:[1,1,1]
	v_add_f32_dpp v192, v192, v192 row_ror:4 row_mask:0xf bank_mask:0xf
	v_pk_fma_f32 v[124:125], v[148:149], v[142:143], v[124:125] op_sel_hi:[0,1,1]
	v_pk_fma_f32 v[128:129], v[148:149], v[142:143], v[128:129] op_sel:[1,0,0] op_sel_hi:[1,1,1]
	ds_write_b32 v204, v196 offset:1360
	v_add_f32_dpp v192, v192, v192 row_ror:8 row_mask:0xf bank_mask:0xf
	ds_write_b32 v206, v198 offset:1360
	ds_read_b128 v[172:175], v30 offset:8192
	ds_read_b128 v[176:179], v30 offset:8448
	ds_read_b128 v[180:183], v30 offset:8704
	ds_read_b128 v[184:187], v30 offset:8960
	ds_read_b32 v188, v31 offset:1024
	ds_read_b32 v189, v205 offset:1024
	v_mov_b32_dpp v194, v192 quad_perm:[1,0,3,2] row_mask:0xf bank_mask:0xf
	v_pk_fma_f32 v[122:123], v[192:193], v[136:137], v[122:123] op_sel_hi:[0,1,1]
	v_pk_fma_f32 v[126:127], v[194:195], v[136:137], v[126:127] op_sel_hi:[0,1,1]
	v_pk_fma_f32 v[124:125], v[192:193], v[138:139], v[124:125] op_sel_hi:[0,1,1]
	v_pk_fma_f32 v[128:129], v[194:195], v[138:139], v[128:129] op_sel_hi:[0,1,1]
	s_waitcnt lgkmcnt(13)
	v_pk_mul_f32 v[192:193], v[122:123], v[152:153]
	v_pk_mul_f32 v[194:195], v[126:127], v[152:153]
	v_pk_fma_f32 v[192:193], v[124:125], v[154:155], v[192:193]
	v_pk_fma_f32 v[194:195], v[128:129], v[154:155], v[194:195]
	v_add_f32_e32 v192, v192, v193
	v_add_f32_e32 v194, v194, v195
	v_pk_mul_f32 v[196:197], v[122:123], v[144:145]
	v_pk_mul_f32 v[198:199], v[126:127], v[144:145]
	v_pk_fma_f32 v[196:197], v[124:125], v[146:147], v[196:197]
	v_add_f32_dpp v192, v194, v192 quad_perm:[1,0,3,2] row_mask:0xf bank_mask:0xf
	v_pk_fma_f32 v[198:199], v[128:129], v[146:147], v[198:199]
	v_add_f32_e32 v196, v196, v197
	v_add_f32_e32 v198, v198, v199
	v_add_f32_dpp v192, v192, v192 quad_perm:[2,3,0,1] row_mask:0xf bank_mask:0xf
	s_waitcnt lgkmcnt(8)
	v_pk_fma_f32 v[122:123], v[168:169], v[160:161], v[122:123] op_sel_hi:[0,1,1]
	v_pk_fma_f32 v[126:127], v[168:169], v[160:161], v[126:127] op_sel:[1,0,0] op_sel_hi:[1,1,1]
	v_add_f32_dpp v192, v192, v192 row_ror:4 row_mask:0xf bank_mask:0xf
	v_pk_fma_f32 v[124:125], v[168:169], v[162:163], v[124:125] op_sel_hi:[0,1,1]
	v_pk_fma_f32 v[128:129], v[168:169], v[162:163], v[128:129] op_sel:[1,0,0] op_sel_hi:[1,1,1]
	ds_write_b32 v204, v196 offset:1632
	v_add_f32_dpp v192, v192, v192 row_ror:8 row_mask:0xf bank_mask:0xf
	ds_write_b32 v206, v198 offset:1632
	ds_read_b128 v[132:135], v30 offset:9216
	ds_read_b128 v[136:139], v30 offset:9472
	ds_read_b128 v[140:143], v30 offset:9728
	ds_read_b128 v[144:147], v30 offset:9984
	ds_read_b32 v148, v31 offset:1152
	ds_read_b32 v149, v205 offset:1152
	v_mov_b32_dpp v194, v192 quad_perm:[1,0,3,2] row_mask:0xf bank_mask:0xf
	v_pk_fma_f32 v[122:123], v[192:193], v[156:157], v[122:123] op_sel_hi:[0,1,1]
	v_pk_fma_f32 v[126:127], v[194:195], v[156:157], v[126:127] op_sel_hi:[0,1,1]
	v_pk_fma_f32 v[124:125], v[192:193], v[158:159], v[124:125] op_sel_hi:[0,1,1]
	v_pk_fma_f32 v[128:129], v[194:195], v[158:159], v[128:129] op_sel_hi:[0,1,1]
	s_waitcnt lgkmcnt(13)
	v_pk_mul_f32 v[192:193], v[122:123], v[172:173]
	v_pk_mul_f32 v[194:195], v[126:127], v[172:173]
	v_pk_fma_f32 v[192:193], v[124:125], v[174:175], v[192:193]
	v_pk_fma_f32 v[194:195], v[128:129], v[174:175], v[194:195]
	v_add_f32_e32 v192, v192, v193
	v_add_f32_e32 v194, v194, v195
	v_pk_mul_f32 v[196:197], v[122:123], v[164:165]
	v_pk_mul_f32 v[198:199], v[126:127], v[164:165]
	v_pk_fma_f32 v[196:197], v[124:125], v[166:167], v[196:197]
	v_add_f32_dpp v192, v194, v192 quad_perm:[1,0,3,2] row_mask:0xf bank_mask:0xf
	v_pk_fma_f32 v[198:199], v[128:129], v[166:167], v[198:199]
	v_add_f32_e32 v196, v196, v197
	v_add_f32_e32 v198, v198, v199
	v_add_f32_dpp v192, v192, v192 quad_perm:[2,3,0,1] row_mask:0xf bank_mask:0xf
	s_waitcnt lgkmcnt(8)
; #define LAS __attribute__((address_space(3)))
; __device__ __forceinline__ void scan_unit(const Args& A, LAS unsigned char* lds, int s, int tid) {
;     ...
;             const LAS float* st = cur + 4 * jq; const LAS float* vp = cur + SC_V_OFF + rl;
;             f32x4 a = *(const LAS f32x4*)(st), bb = *(const LAS f32x4*)(st + 64), k = *(const LAS f32x4*)(st + 128), r = *(const LAS f32x4*)(st + 192);
;             float v = vp[0];
;             f32x4 a1 = *(const LAS f32x4*)(st + SC_STEP_F), bb1 = *(const LAS f32x4*)(st + SC_STEP_F + 64), k1 = *(const LAS f32x4*)(st + SC_STEP_F + 128), r1 = *(const LAS f32x4*)(st + SC_STEP_F + 192);
;             float v1 = vp[32];
;             f32x4 pr = (f32x4){0.f, 0.f, 0.f, 0.f};
; #pragma unroll
;             for (int tl = 0; tl < SC_TC; ++tl) {
;                 float sa, yy;
;                 asm volatile(
;                     "v_mul_f32_e32 %0, %2, %6\n\t"
;                     "v_mul_f32_e32 %1, %2, %10\n\t"
;                     "v_fmac_f32_e32 %0, %3, %7\n\t"
;                     "v_fmac_f32_e32 %1, %3, %11\n\t"
;                     "v_fmac_f32_e32 %0, %4, %8\n\t"
;                     "v_fmac_f32_e32 %1, %4, %12\n\t"
;                     "v_fmac_f32_e32 %0, %5, %9\n\t"
;                     "v_fmac_f32_e32 %1, %5, %13\n\t"
;                     "v_fmac_f32_e32 %2, %18, %14\n\t"
;                     "v_add_f32_dpp %0, %0, %0 quad_perm:[1,0,3,2] row_mask:0xf bank_mask:0xf\n\t"
;                     "v_fmac_f32_e32 %3, %18, %15\n\t"
;                     "v_fmac_f32_e32 %4, %18, %16\n\t"
;                     "v_add_f32_dpp %0, %0, %0 quad_perm:[2,3,0,1] row_mask:0xf bank_mask:0xf\n\t"
;                     "v_fmac_f32_e32 %5, %18, %17\n\t"
;                     "s_nop 0\n\t"
;                     "v_add_f32_dpp %0, %0, %0 row_half_mirror row_mask:0xf bank_mask:0xf\n\t"
;                     : "=&v"(sa), "=&v"(yy), "+v"(S0), "+v"(S1), "+v"(S2), "+v"(S3)
;                     : "v"(a.x), "v"(a.y), "v"(a.z), "v"(a.w), "v"(pr.x), "v"(pr.y), "v"(pr.z), "v"(pr.w), "v"(k.x), "v"(k.y), "v"(k.z), "v"(k.w), "v"(v));
;                 if (tl > 0) yb[(tl - 1) * SC_YS + lane] = yy;
;                 const f32x4 b_now = bb; pr = r;
;                 a = a1; bb = bb1; k = k1; r = r1; v = v1;
;                 if (tl + 2 < SC_TC) { const LAS float* sn = st + (tl + 2) * SC_STEP_F;
	v_pk_fma_f32 v[122:123], v[188:189], v[180:181], v[122:123] op_sel_hi:[0,1,1]
	v_pk_fma_f32 v[126:127], v[188:189], v[180:181], v[126:127] op_sel:[1,0,0] op_sel_hi:[1,1,1]
	v_add_f32_dpp v192, v192, v192 row_ror:4 row_mask:0xf bank_mask:0xf
	v_pk_fma_f32 v[124:125], v[188:189], v[182:183], v[124:125] op_sel_hi:[0,1,1]
	v_pk_fma_f32 v[128:129], v[188:189], v[182:183], v[128:129] op_sel:[1,0,0] op_sel_hi:[1,1,1]
	ds_write_b32 v204, v196 offset:1904
	v_add_f32_dpp v192, v192, v192 row_ror:8 row_mask:0xf bank_mask:0xf
	ds_write_b32 v206, v198 offset:1904
	ds_read_b128 v[152:155], v30 offset:10240
	ds_read_b128 v[156:159], v30 offset:10496
	ds_read_b128 v[160:163], v30 offset:10752
	ds_read_b128 v[164:167], v30 offset:11008
	ds_read_b32 v168, v31 offset:1280
	ds_read_b32 v169, v205 offset:1280
	v_mov_b32_dpp v194, v192 quad_perm:[1,0,3,2] row_mask:0xf bank_mask:0xf
	v_pk_fma_f32 v[122:123], v[192:193], v[176:177], v[122:123] op_sel_hi:[0,1,1]
	v_pk_fma_f32 v[126:127], v[194:195], v[176:177], v[126:127] op_sel_hi:[0,1,1]
	v_pk_fma_f32 v[124:125], v[192:193], v[178:179], v[124:125] op_sel_hi:[0,1,1]
	v_pk_fma_f32 v[128:129], v[194:195], v[178:179], v[128:129] op_sel_hi:[0,1,1]
	s_waitcnt lgkmcnt(13)
	v_pk_mul_f32 v[192:193], v[122:123], v[132:133]
	v_pk_mul_f32 v[194:195], v[126:127], v[132:133]
	v_pk_fma_f32 v[192:193], v[124:125], v[134:135], v[192:193]
	v_pk_fma_f32 v[194:195], v[128:129], v[134:135], v[194:195]
	v_add_f32_e32 v192, v192, v193
	v_add_f32_e32 v194, v194, v195
	v_pk_mul_f32 v[196:197], v[122:123], v[184:185]
	v_pk_mul_f32 v[198:199], v[126:127], v[184:185]
	v_pk_fma_f32 v[196:197], v[124:125], v[186:187], v[196:197]
	v_add_f32_dpp v192, v194, v192 quad_perm:[1,0,3,2] row_mask:0xf bank_mask:0xf
	v_pk_fma_f32 v[198:199], v[128:129], v[186:187], v[198:199]
	v_add_f32_e32 v196, v196, v197
	v_add_f32_e32 v198, v198, v199
	v_add_f32_dpp v192, v192, v192 quad_perm:[2,3,0,1] row_mask:0xf bank_mask:0xf
	s_waitcnt lgkmcnt(8)
	v_pk_fma_f32 v[122:123], v[148:149], v[140:141], v[122:123] op_sel_hi:[0,1,1]
	v_pk_fma_f32 v[126:127], v[148:149], v[140:141], v[126:127] op_sel:[1,0,0] op_sel_hi:[1,1,1]
	v_add_f32_dpp v192, v192, v192 row_ror:4 row_mask:0xf bank_mask:0xf
	v_pk_fma_f32 v[124:125], v[148:149], v[142:143], v[124:125] op_sel_hi:[0,1,1]
	v_pk_fma_f32 v[128:129], v[148:149], v[142:143], v[128:129] op_sel:[1,0,0] op_sel_hi:[1,1,1]
	ds_write_b32 v204, v196 offset:2176
	v_add_f32_dpp v192, v192, v192 row_ror:8 row_mask:0xf bank_mask:0xf
	ds_write_b32 v206, v198 offset:2176
	ds_read_b128 v[172:175], v30 offset:11264
	ds_read_b128 v[176:179], v30 offset:11520
	ds_read_b128 v[180:183], v30 offset:11776
	ds_read_b128 v[184:187], v30 offset:12032
	ds_read_b32 v188, v31 offset:1408
	ds_read_b32 v189, v205 offset:1408
	v_mov_b32_dpp v194, v192 quad_perm:[1,0,3,2] row_mask:0xf bank_mask:0xf
	v_pk_fma_f32 v[122:123], v[192:193], v[136:137], v[122:123] op_sel_hi:[0,1,1]
	v_pk_fma_f32 v[126:127], v[194:195], v[136:137], v[126:127] op_sel_hi:[0,1,1]
	v_pk_fma_f32 v[124:125], v[192:193], v[138:139], v[124:125] op_sel_hi:[0,1,1]
	v_pk_fma_f32 v[128:129], v[194:195], v[138:139], v[128:129] op_sel_hi:[0,1,1]
	s_waitcnt lgkmcnt(13)
	v_pk_mul_f32 v[192:193], v[122:123], v[152:153]
	v_pk_mul_f32 v[194:195], v[126:127], v[152:153]
	v_pk_fma_f32 v[192:193], v[124:125], v[154:155], v[192:193]
	v_pk_fma_f32 v[194:195], v[128:129], v[154:155], v[194:195]
	v_add_f32_e32 v192, v192, v193
	v_add_f32_e32 v194, v194, v195
	v_pk_mul_f32 v[196:197], v[122:123], v[144:145]
	v_pk_mul_f32 v[198:199], v[126:127], v[144:145]
	v_pk_fma_f32 v[196:197], v[124:125], v[146:147], v[196:197]
	v_add_f32_dpp v192, v194, v192 quad_perm:[1,0,3,2] row_mask:0xf bank_mask:0xf
	v_pk_fma_f32 v[198:199], v[128:129], v[146:147], v[198:199]
	v_add_f32_e32 v196, v196, v197
	v_add_f32_e32 v198, v198, v199
	v_add_f32_dpp v192, v192, v192 quad_perm:[2,3,0,1] row_mask:0xf bank_mask:0xf
	s_waitcnt lgkmcnt(8)
	v_pk_fma_f32 v[122:123], v[168:169], v[160:161], v[122:123] op_sel_hi:[0,1,1]
	v_pk_fma_f32 v[126:127], v[168:169], v[160:161], v[126:127] op_sel:[1,0,0] op_sel_hi:[1,1,1]
	v_add_f32_dpp v192, v192, v192 row_ror:4 row_mask:0xf bank_mask:0xf
	v_pk_fma_f32 v[124:125], v[168:169], v[162:163], v[124:125] op_sel_hi:[0,1,1]
	v_pk_fma_f32 v[128:129], v[168:169], v[162:163], v[128:129] op_sel:[1,0,0] op_sel_hi:[1,1,1]
	ds_write_b32 v204, v196 offset:2448
	v_add_f32_dpp v192, v192, v192 row_ror:8 row_mask:0xf bank_mask:0xf
	ds_write_b32 v206, v198 offset:2448
	ds_read_b128 v[132:135], v30 offset:12288
	ds_read_b128 v[136:139], v30 offset:12544
	ds_read_b128 v[140:143], v30 offset:12800
	ds_read_b128 v[144:147], v30 offset:13056
	ds_read_b32 v148, v31 offset:1536
	ds_read_b32 v149, v205 offset:1536
	v_mov_b32_dpp v194, v192 quad_perm:[1,0,3,2] row_mask:0xf bank_mask:0xf
	v_pk_fma_f32 v[122:123], v[192:193], v[156:157], v[122:123] op_sel_hi:[0,1,1]
	v_pk_fma_f32 v[126:127], v[194:195], v[156:157], v[126:127] op_sel_hi:[0,1,1]
	v_pk_fma_f32 v[124:125], v[192:193], v[158:159], v[124:125] op_sel_hi:[0,1,1]
	v_pk_fma_f32 v[128:129], v[194:195], v[158:159], v[128:129] op_sel_hi:[0,1,1]
	s_waitcnt lgkmcnt(13)
	v_pk_mul_f32 v[192:193], v[122:123], v[172:173]
	v_pk_mul_f32 v[194:195], v[126:127], v[172:173]
	v_pk_fma_f32 v[192:193], v[124:125], v[174:175], v[192:193]
	v_pk_fma_f32 v[194:195], v[128:129], v[174:175], v[194:195]
	v_add_f32_e32 v192, v192, v193
	v_add_f32_e32 v194, v194, v195
	v_pk_mul_f32 v[196:197], v[122:123], v[164:165]
	v_pk_mul_f32 v[198:199], v[126:127], v[164:165]
	v_pk_fma_f32 v[196:197], v[124:125], v[166:167], v[196:197]
	v_add_f32_dpp v192, v194, v192 quad_perm:[1,0,3,2] row_mask:0xf bank_mask:0xf
	v_pk_fma_f32 v[198:199], v[128:129], v[166:167], v[198:199]
	v_add_f32_e32 v196, v196, v197
	v_add_f32_e32 v198, v198, v199
	v_add_f32_dpp v192, v192, v192 quad_perm:[2,3,0,1] row_mask:0xf bank_mask:0xf
	s_waitcnt lgkmcnt(8)
; #define LAS __attribute__((address_space(3)))
; __device__ __forceinline__ void scan_unit(const Args& A, LAS unsigned char* lds, int s, int tid) {
;     ...
;             const LAS float* st = cur + 4 * jq; const LAS float* vp = cur + SC_V_OFF + rl;
;             f32x4 a = *(const LAS f32x4*)(st), bb = *(const LAS f32x4*)(st + 64), k = *(const LAS f32x4*)(st + 128), r = *(const LAS f32x4*)(st + 192);
;             float v = vp[0];
;             f32x4 a1 = *(const LAS f32x4*)(st + SC_STEP_F), bb1 = *(const LAS f32x4*)(st + SC_STEP_F + 64), k1 = *(const LAS f32x4*)(st + SC_STEP_F + 128), r1 = *(const LAS f32x4*)(st + SC_STEP_F + 192);
;             float v1 = vp[32];
;             f32x4 pr = (f32x4){0.f, 0.f, 0.f, 0.f};
; #pragma unroll
;             for (int tl = 0; tl < SC_TC; ++tl) {
;                 float sa, yy;
;                 asm volatile(
;                     "v_mul_f32_e32 %0, %2, %6\n\t"
;                     "v_mul_f32_e32 %1, %2, %10\n\t"
;                     "v_fmac_f32_e32 %0, %3, %7\n\t"
;                     "v_fmac_f32_e32 %1, %3, %11\n\t"
;                     "v_fmac_f32_e32 %0, %4, %8\n\t"
;                     "v_fmac_f32_e32 %1, %4, %12\n\t"
;                     "v_fmac_f32_e32 %0, %5, %9\n\t"
;                     "v_fmac_f32_e32 %1, %5, %13\n\t"
;                     "v_fmac_f32_e32 %2, %18, %14\n\t"
;                     "v_add_f32_dpp %0, %0, %0 quad_perm:[1,0,3,2] row_mask:0xf bank_mask:0xf\n\t"
;                     "v_fmac_f32_e32 %3, %18, %15\n\t"
;                     "v_fmac_f32_e32 %4, %18, %16\n\t"
;                     "v_add_f32_dpp %0, %0, %0 quad_perm:[2,3,0,1] row_mask:0xf bank_mask:0xf\n\t"
;                     "v_fmac_f32_e32 %5, %18, %17\n\t"
;                     "s_nop 0\n\t"
;                     "v_add_f32_dpp %0, %0, %0 row_half_mirror row_mask:0xf bank_mask:0xf\n\t"
;                     : "=&v"(sa), "=&v"(yy), "+v"(S0), "+v"(S1), "+v"(S2), "+v"(S3)
;                     : "v"(a.x), "v"(a.y), "v"(a.z), "v"(a.w), "v"(pr.x), "v"(pr.y), "v"(pr.z), "v"(pr.w), "v"(k.x), "v"(k.y), "v"(k.z), "v"(k.w), "v"(v));
;                 if (tl > 0) yb[(tl - 1) * SC_YS + lane] = yy;
;                 const f32x4 b_now = bb; pr = r;
;                 a = a1; bb = bb1; k = k1; r = r1; v = v1;
;                 if (tl + 2 < SC_TC) { const LAS float* sn = st + (tl + 2) * SC_STEP_F;
	v_pk_fma_f32 v[122:123], v[188:189], v[180:181], v[122:123] op_sel_hi:[0,1,1]
	v_pk_fma_f32 v[126:127], v[188:189], v[180:181], v[126:127] op_sel:[1,0,0] op_sel_hi:[1,1,1]
	v_add_f32_dpp v192, v192, v192 row_ror:4 row_mask:0xf bank_mask:0xf
	v_pk_fma_f32 v[124:125], v[188:189], v[182:183], v[124:125] op_sel_hi:[0,1,1]
	v_pk_fma_f32 v[128:129], v[188:189], v[182:183], v[128:129] op_sel:[1,0,0] op_sel_hi:[1,1,1]
	ds_write_b32 v204, v196 offset:2720
	v_add_f32_dpp v192, v192, v192 row_ror:8 row_mask:0xf bank_mask:0xf
	ds_write_b32 v206, v198 offset:2720
	ds_read_b128 v[152:155], v30 offset:13312
	ds_read_b128 v[156:159], v30 offset:13568
	ds_read_b128 v[160:163], v30 offset:13824
	ds_read_b128 v[164:167], v30 offset:14080
	ds_read_b32 v168, v31 offset:1664
	ds_read_b32 v169, v205 offset:1664
	v_mov_b32_dpp v194, v192 quad_perm:[1,0,3,2] row_mask:0xf bank_mask:0xf
	v_pk_fma_f32 v[122:123], v[192:193], v[176:177], v[122:123] op_sel_hi:[0,1,1]
	v_pk_fma_f32 v[126:127], v[194:195], v[176:177], v[126:127] op_sel_hi:[0,1,1]
	v_pk_fma_f32 v[124:125], v[192:193], v[178:179], v[124:125] op_sel_hi:[0,1,1]
	v_pk_fma_f32 v[128:129], v[194:195], v[178:179], v[128:129] op_sel_hi:[0,1,1]
	s_waitcnt lgkmcnt(13)
	v_pk_mul_f32 v[192:193], v[122:123], v[132:133]
	v_pk_mul_f32 v[194:195], v[126:127], v[132:133]
	v_pk_fma_f32 v[192:193], v[124:125], v[134:135], v[192:193]
	v_pk_fma_f32 v[194:195], v[128:129], v[134:135], v[194:195]
	v_add_f32_e32 v192, v192, v193
	v_add_f32_e32 v194, v194, v195
	v_pk_mul_f32 v[196:197], v[122:123], v[184:185]
	v_pk_mul_f32 v[198:199], v[126:127], v[184:185]
	v_pk_fma_f32 v[196:197], v[124:125], v[186:187], v[196:197]
	v_add_f32_dpp v192, v194, v192 quad_perm:[1,0,3,2] row_mask:0xf bank_mask:0xf
	v_pk_fma_f32 v[198:199], v[128:129], v[186:187], v[198:199]
	v_add_f32_e32 v196, v196, v197
	v_add_f32_e32 v198, v198, v199
	v_add_f32_dpp v192, v192, v192 quad_perm:[2,3,0,1] row_mask:0xf bank_mask:0xf
	s_waitcnt lgkmcnt(8)
	v_pk_fma_f32 v[122:123], v[148:149], v[140:141], v[122:123] op_sel_hi:[0,1,1]
	v_pk_fma_f32 v[126:127], v[148:149], v[140:141], v[126:127] op_sel:[1,0,0] op_sel_hi:[1,1,1]
	v_add_f32_dpp v192, v192, v192 row_ror:4 row_mask:0xf bank_mask:0xf
	v_pk_fma_f32 v[124:125], v[148:149], v[142:143], v[124:125] op_sel_hi:[0,1,1]
	v_pk_fma_f32 v[128:129], v[148:149], v[142:143], v[128:129] op_sel:[1,0,0] op_sel_hi:[1,1,1]
	ds_write_b32 v204, v196 offset:2992
	v_add_f32_dpp v192, v192, v192 row_ror:8 row_mask:0xf bank_mask:0xf
	ds_write_b32 v206, v198 offset:2992
	ds_read_b128 v[172:175], v30 offset:14336
	ds_read_b128 v[176:179], v30 offset:14592
	ds_read_b128 v[180:183], v30 offset:14848
	ds_read_b128 v[184:187], v30 offset:15104
	ds_read_b32 v188, v31 offset:1792
	ds_read_b32 v189, v205 offset:1792
	v_mov_b32_dpp v194, v192 quad_perm:[1,0,3,2] row_mask:0xf bank_mask:0xf
	v_pk_fma_f32 v[122:123], v[192:193], v[136:137], v[122:123] op_sel_hi:[0,1,1]
	v_pk_fma_f32 v[126:127], v[194:195], v[136:137], v[126:127] op_sel_hi:[0,1,1]
	v_pk_fma_f32 v[124:125], v[192:193], v[138:139], v[124:125] op_sel_hi:[0,1,1]
	v_pk_fma_f32 v[128:129], v[194:195], v[138:139], v[128:129] op_sel_hi:[0,1,1]
	s_waitcnt lgkmcnt(13)
	v_pk_mul_f32 v[192:193], v[122:123], v[152:153]
	v_pk_mul_f32 v[194:195], v[126:127], v[152:153]
	v_pk_fma_f32 v[192:193], v[124:125], v[154:155], v[192:193]
	v_pk_fma_f32 v[194:195], v[128:129], v[154:155], v[194:195]
	v_add_f32_e32 v192, v192, v193
	v_add_f32_e32 v194, v194, v195
	v_pk_mul_f32 v[196:197], v[122:123], v[144:145]
	v_pk_mul_f32 v[198:199], v[126:127], v[144:145]
	v_pk_fma_f32 v[196:197], v[124:125], v[146:147], v[196:197]
	v_add_f32_dpp v192, v194, v192 quad_perm:[1,0,3,2] row_mask:0xf bank_mask:0xf
	v_pk_fma_f32 v[198:199], v[128:129], v[146:147], v[198:199]
	v_add_f32_e32 v196, v196, v197
	v_add_f32_e32 v198, v198, v199
	v_add_f32_dpp v192, v192, v192 quad_perm:[2,3,0,1] row_mask:0xf bank_mask:0xf
	s_waitcnt lgkmcnt(8)
	v_pk_fma_f32 v[122:123], v[168:169], v[160:161], v[122:123] op_sel_hi:[0,1,1]
	v_pk_fma_f32 v[126:127], v[168:169], v[160:161], v[126:127] op_sel:[1,0,0] op_sel_hi:[1,1,1]
	v_add_f32_dpp v192, v192, v192 row_ror:4 row_mask:0xf bank_mask:0xf
	v_pk_fma_f32 v[124:125], v[168:169], v[162:163], v[124:125] op_sel_hi:[0,1,1]
	v_pk_fma_f32 v[128:129], v[168:169], v[162:163], v[128:129] op_sel:[1,0,0] op_sel_hi:[1,1,1]
	ds_write_b32 v204, v196 offset:3264
	v_add_f32_dpp v192, v192, v192 row_ror:8 row_mask:0xf bank_mask:0xf
	ds_write_b32 v206, v198 offset:3264
	ds_read_b128 v[132:135], v30 offset:15360
	ds_read_b128 v[136:139], v30 offset:15616
	ds_read_b128 v[140:143], v30 offset:15872
	ds_read_b128 v[144:147], v30 offset:16128
	ds_read_b32 v148, v31 offset:1920
	ds_read_b32 v149, v205 offset:1920
	v_mov_b32_dpp v194, v192 quad_perm:[1,0,3,2] row_mask:0xf bank_mask:0xf
	v_pk_fma_f32 v[122:123], v[192:193], v[156:157], v[122:123] op_sel_hi:[0,1,1]
	v_pk_fma_f32 v[126:127], v[194:195], v[156:157], v[126:127] op_sel_hi:[0,1,1]
	v_pk_fma_f32 v[124:125], v[192:193], v[158:159], v[124:125] op_sel_hi:[0,1,1]
	v_pk_fma_f32 v[128:129], v[194:195], v[158:159], v[128:129] op_sel_hi:[0,1,1]
	s_waitcnt lgkmcnt(13)
	v_pk_mul_f32 v[192:193], v[122:123], v[172:173]
	v_pk_mul_f32 v[194:195], v[126:127], v[172:173]
	v_pk_fma_f32 v[192:193], v[124:125], v[174:175], v[192:193]
	v_pk_fma_f32 v[194:195], v[128:129], v[174:175], v[194:195]
	v_add_f32_e32 v192, v192, v193
	v_add_f32_e32 v194, v194, v195
	v_pk_mul_f32 v[196:197], v[122:123], v[164:165]
	v_pk_mul_f32 v[198:199], v[126:127], v[164:165]
	v_pk_fma_f32 v[196:197], v[124:125], v[166:167], v[196:197]
	v_add_f32_dpp v192, v194, v192 quad_perm:[1,0,3,2] row_mask:0xf bank_mask:0xf
	v_pk_fma_f32 v[198:199], v[128:129], v[166:167], v[198:199]
	v_add_f32_e32 v196, v196, v197
	v_add_f32_e32 v198, v198, v199
	v_add_f32_dpp v192, v192, v192 quad_perm:[2,3,0,1] row_mask:0xf bank_mask:0xf
	s_waitcnt lgkmcnt(8)
; #define LAS __attribute__((address_space(3)))
; __device__ __forceinline__ void scan_unit(const Args& A, LAS unsigned char* lds, int s, int tid) {
;     ...
;             const LAS float* st = cur + 4 * jq; const LAS float* vp = cur + SC_V_OFF + rl;
;             f32x4 a = *(const LAS f32x4*)(st), bb = *(const LAS f32x4*)(st + 64), k = *(const LAS f32x4*)(st + 128), r = *(const LAS f32x4*)(st + 192);
;             float v = vp[0];
;             f32x4 a1 = *(const LAS f32x4*)(st + SC_STEP_F), bb1 = *(const LAS f32x4*)(st + SC_STEP_F + 64), k1 = *(const LAS f32x4*)(st + SC_STEP_F + 128), r1 = *(const LAS f32x4*)(st + SC_STEP_F + 192);
;             float v1 = vp[32];
;             f32x4 pr = (f32x4){0.f, 0.f, 0.f, 0.f};
; #pragma unroll
;             for (int tl = 0; tl < SC_TC; ++tl) {
;                 float sa, yy;
;                 asm volatile(
;                     "v_mul_f32_e32 %0, %2, %6\n\t"
;                     "v_mul_f32_e32 %1, %2, %10\n\t"
;                     "v_fmac_f32_e32 %0, %3, %7\n\t"
;                     "v_fmac_f32_e32 %1, %3, %11\n\t"
;                     "v_fmac_f32_e32 %0, %4, %8\n\t"
;                     "v_fmac_f32_e32 %1, %4, %12\n\t"
;                     "v_fmac_f32_e32 %0, %5, %9\n\t"
;                     "v_fmac_f32_e32 %1, %5, %13\n\t"
;                     "v_fmac_f32_e32 %2, %18, %14\n\t"
;                     "v_add_f32_dpp %0, %0, %0 quad_perm:[1,0,3,2] row_mask:0xf bank_mask:0xf\n\t"
;                     "v_fmac_f32_e32 %3, %18, %15\n\t"
;                     "v_fmac_f32_e32 %4, %18, %16\n\t"
;                     "v_add_f32_dpp %0, %0, %0 quad_perm:[2,3,0,1] row_mask:0xf bank_mask:0xf\n\t"
;                     "v_fmac_f32_e32 %5, %18, %17\n\t"
;                     "s_nop 0\n\t"
;                     "v_add_f32_dpp %0, %0, %0 row_half_mirror row_mask:0xf bank_mask:0xf\n\t"
;                     : "=&v"(sa), "=&v"(yy), "+v"(S0), "+v"(S1), "+v"(S2), "+v"(S3)
;                     : "v"(a.x), "v"(a.y), "v"(a.z), "v"(a.w), "v"(pr.x), "v"(pr.y), "v"(pr.z), "v"(pr.w), "v"(k.x), "v"(k.y), "v"(k.z), "v"(k.w), "v"(v));
;                 if (tl > 0) yb[(tl - 1) * SC_YS + lane] = yy;
;                 const f32x4 b_now = bb; pr = r;
;                 a = a1; bb = bb1; k = k1; r = r1; v = v1;
;                 if (tl + 2 < SC_TC) { const LAS float* sn = st + (tl + 2) * SC_STEP_F;
	v_pk_fma_f32 v[122:123], v[188:189], v[180:181], v[122:123] op_sel_hi:[0,1,1]
	v_pk_fma_f32 v[126:127], v[188:189], v[180:181], v[126:127] op_sel:[1,0,0] op_sel_hi:[1,1,1]
	v_add_f32_dpp v192, v192, v192 row_ror:4 row_mask:0xf bank_mask:0xf
	v_pk_fma_f32 v[124:125], v[188:189], v[182:183], v[124:125] op_sel_hi:[0,1,1]
	v_pk_fma_f32 v[128:129], v[188:189], v[182:183], v[128:129] op_sel:[1,0,0] op_sel_hi:[1,1,1]
	ds_write_b32 v204, v196 offset:3536
	v_add_f32_dpp v192, v192, v192 row_ror:8 row_mask:0xf bank_mask:0xf
	ds_write_b32 v206, v198 offset:3536
	ds_read_b128 v[152:155], v30 offset:16384
	ds_read_b128 v[156:159], v30 offset:16640
	ds_read_b128 v[160:163], v30 offset:16896
	ds_read_b128 v[164:167], v30 offset:17152
	ds_read_b32 v168, v31 offset:2048
	ds_read_b32 v169, v205 offset:2048
	v_mov_b32_dpp v194, v192 quad_perm:[1,0,3,2] row_mask:0xf bank_mask:0xf
	v_pk_fma_f32 v[122:123], v[192:193], v[176:177], v[122:123] op_sel_hi:[0,1,1]
	v_pk_fma_f32 v[126:127], v[194:195], v[176:177], v[126:127] op_sel_hi:[0,1,1]
	v_pk_fma_f32 v[124:125], v[192:193], v[178:179], v[124:125] op_sel_hi:[0,1,1]
	v_pk_fma_f32 v[128:129], v[194:195], v[178:179], v[128:129] op_sel_hi:[0,1,1]
	s_waitcnt lgkmcnt(13)
	v_pk_mul_f32 v[192:193], v[122:123], v[132:133]
	v_pk_mul_f32 v[194:195], v[126:127], v[132:133]
	v_pk_fma_f32 v[192:193], v[124:125], v[134:135], v[192:193]
	v_pk_fma_f32 v[194:195], v[128:129], v[134:135], v[194:195]
	v_add_f32_e32 v192, v192, v193
	v_add_f32_e32 v194, v194, v195
	v_pk_mul_f32 v[196:197], v[122:123], v[184:185]
	v_pk_mul_f32 v[198:199], v[126:127], v[184:185]
	v_pk_fma_f32 v[196:197], v[124:125], v[186:187], v[196:197]
	v_add_f32_dpp v192, v194, v192 quad_perm:[1,0,3,2] row_mask:0xf bank_mask:0xf
	v_pk_fma_f32 v[198:199], v[128:129], v[186:187], v[198:199]
	v_add_f32_e32 v196, v196, v197
	v_add_f32_e32 v198, v198, v199
	v_add_f32_dpp v192, v192, v192 quad_perm:[2,3,0,1] row_mask:0xf bank_mask:0xf
	s_waitcnt lgkmcnt(8)
	v_pk_fma_f32 v[122:123], v[148:149], v[140:141], v[122:123] op_sel_hi:[0,1,1]
	v_pk_fma_f32 v[126:127], v[148:149], v[140:141], v[126:127] op_sel:[1,0,0] op_sel_hi:[1,1,1]
	v_add_f32_dpp v192, v192, v192 row_ror:4 row_mask:0xf bank_mask:0xf
	v_pk_fma_f32 v[124:125], v[148:149], v[142:143], v[124:125] op_sel_hi:[0,1,1]
	v_pk_fma_f32 v[128:129], v[148:149], v[142:143], v[128:129] op_sel:[1,0,0] op_sel_hi:[1,1,1]
	ds_write_b32 v204, v196 offset:3808
	v_add_f32_dpp v192, v192, v192 row_ror:8 row_mask:0xf bank_mask:0xf
	ds_write_b32 v206, v198 offset:3808
	ds_read_b128 v[172:175], v30 offset:17408
	ds_read_b128 v[176:179], v30 offset:17664
	ds_read_b128 v[180:183], v30 offset:17920
	ds_read_b128 v[184:187], v30 offset:18176
	ds_read_b32 v188, v31 offset:2176
	ds_read_b32 v189, v205 offset:2176
	v_mov_b32_dpp v194, v192 quad_perm:[1,0,3,2] row_mask:0xf bank_mask:0xf
	v_pk_fma_f32 v[122:123], v[192:193], v[136:137], v[122:123] op_sel_hi:[0,1,1]
	v_pk_fma_f32 v[126:127], v[194:195], v[136:137], v[126:127] op_sel_hi:[0,1,1]
	v_pk_fma_f32 v[124:125], v[192:193], v[138:139], v[124:125] op_sel_hi:[0,1,1]
	v_pk_fma_f32 v[128:129], v[194:195], v[138:139], v[128:129] op_sel_hi:[0,1,1]
	s_waitcnt lgkmcnt(13)
	v_pk_mul_f32 v[192:193], v[122:123], v[152:153]
	v_pk_mul_f32 v[194:195], v[126:127], v[152:153]
	v_pk_fma_f32 v[192:193], v[124:125], v[154:155], v[192:193]
	v_pk_fma_f32 v[194:195], v[128:129], v[154:155], v[194:195]
	v_add_f32_e32 v192, v192, v193
	v_add_f32_e32 v194, v194, v195
	v_pk_mul_f32 v[196:197], v[122:123], v[144:145]
	v_pk_mul_f32 v[198:199], v[126:127], v[144:145]
	v_pk_fma_f32 v[196:197], v[124:125], v[146:147], v[196:197]
	v_add_f32_dpp v192, v194, v192 quad_perm:[1,0,3,2] row_mask:0xf bank_mask:0xf
	v_pk_fma_f32 v[198:199], v[128:129], v[146:147], v[198:199]
	v_add_f32_e32 v196, v196, v197
	v_add_f32_e32 v198, v198, v199
	v_add_f32_dpp v192, v192, v192 quad_perm:[2,3,0,1] row_mask:0xf bank_mask:0xf
	s_waitcnt lgkmcnt(8)
	v_pk_fma_f32 v[122:123], v[168:169], v[160:161], v[122:123] op_sel_hi:[0,1,1]
	v_pk_fma_f32 v[126:127], v[168:169], v[160:161], v[126:127] op_sel:[1,0,0] op_sel_hi:[1,1,1]
	v_add_f32_dpp v192, v192, v192 row_ror:4 row_mask:0xf bank_mask:0xf
	v_pk_fma_f32 v[124:125], v[168:169], v[162:163], v[124:125] op_sel_hi:[0,1,1]
	v_pk_fma_f32 v[128:129], v[168:169], v[162:163], v[128:129] op_sel:[1,0,0] op_sel_hi:[1,1,1]
	ds_write_b32 v204, v196 offset:4080
	v_add_f32_dpp v192, v192, v192 row_ror:8 row_mask:0xf bank_mask:0xf
	ds_write_b32 v206, v198 offset:4080
	ds_read_b128 v[132:135], v30 offset:18432
	ds_read_b128 v[136:139], v30 offset:18688
	ds_read_b128 v[140:143], v30 offset:18944
	ds_read_b128 v[144:147], v30 offset:19200
	ds_read_b32 v148, v31 offset:2304
	ds_read_b32 v149, v205 offset:2304
	v_mov_b32_dpp v194, v192 quad_perm:[1,0,3,2] row_mask:0xf bank_mask:0xf
	v_pk_fma_f32 v[122:123], v[192:193], v[156:157], v[122:123] op_sel_hi:[0,1,1]
	v_pk_fma_f32 v[126:127], v[194:195], v[156:157], v[126:127] op_sel_hi:[0,1,1]
	v_pk_fma_f32 v[124:125], v[192:193], v[158:159], v[124:125] op_sel_hi:[0,1,1]
	v_pk_fma_f32 v[128:129], v[194:195], v[158:159], v[128:129] op_sel_hi:[0,1,1]
	s_waitcnt lgkmcnt(13)
	v_pk_mul_f32 v[192:193], v[122:123], v[172:173]
	v_pk_mul_f32 v[194:195], v[126:127], v[172:173]
	v_pk_fma_f32 v[192:193], v[124:125], v[174:175], v[192:193]
	v_pk_fma_f32 v[194:195], v[128:129], v[174:175], v[194:195]
	v_add_f32_e32 v192, v192, v193
	v_add_f32_e32 v194, v194, v195
	v_pk_mul_f32 v[196:197], v[122:123], v[164:165]
	v_pk_mul_f32 v[198:199], v[126:127], v[164:165]
	v_pk_fma_f32 v[196:197], v[124:125], v[166:167], v[196:197]
	v_add_f32_dpp v192, v194, v192 quad_perm:[1,0,3,2] row_mask:0xf bank_mask:0xf
	v_pk_fma_f32 v[198:199], v[128:129], v[166:167], v[198:199]
	v_add_f32_e32 v196, v196, v197
	v_add_f32_e32 v198, v198, v199
	v_add_f32_dpp v192, v192, v192 quad_perm:[2,3,0,1] row_mask:0xf bank_mask:0xf
	s_waitcnt lgkmcnt(8)
; #define LAS __attribute__((address_space(3)))
; __device__ __forceinline__ void scan_unit(const Args& A, LAS unsigned char* lds, int s, int tid) {
;     ...
;             const LAS float* st = cur + 4 * jq; const LAS float* vp = cur + SC_V_OFF + rl;
;             f32x4 a = *(const LAS f32x4*)(st), bb = *(const LAS f32x4*)(st + 64), k = *(const LAS f32x4*)(st + 128), r = *(const LAS f32x4*)(st + 192);
;             float v = vp[0];
;             f32x4 a1 = *(const LAS f32x4*)(st + SC_STEP_F), bb1 = *(const LAS f32x4*)(st + SC_STEP_F + 64), k1 = *(const LAS f32x4*)(st + SC_STEP_F + 128), r1 = *(const LAS f32x4*)(st + SC_STEP_F + 192);
;             float v1 = vp[32];
;             f32x4 pr = (f32x4){0.f, 0.f, 0.f, 0.f};
; #pragma unroll
;             for (int tl = 0; tl < SC_TC; ++tl) {
;                 float sa, yy;
;                 asm volatile(
;                     "v_mul_f32_e32 %0, %2, %6\n\t"
;                     "v_mul_f32_e32 %1, %2, %10\n\t"
;                     "v_fmac_f32_e32 %0, %3, %7\n\t"
;                     "v_fmac_f32_e32 %1, %3, %11\n\t"
;                     "v_fmac_f32_e32 %0, %4, %8\n\t"
;                     "v_fmac_f32_e32 %1, %4, %12\n\t"
;                     "v_fmac_f32_e32 %0, %5, %9\n\t"
;                     "v_fmac_f32_e32 %1, %5, %13\n\t"
;                     "v_fmac_f32_e32 %2, %18, %14\n\t"
;                     "v_add_f32_dpp %0, %0, %0 quad_perm:[1,0,3,2] row_mask:0xf bank_mask:0xf\n\t"
;                     "v_fmac_f32_e32 %3, %18, %15\n\t"
;                     "v_fmac_f32_e32 %4, %18, %16\n\t"
;                     "v_add_f32_dpp %0, %0, %0 quad_perm:[2,3,0,1] row_mask:0xf bank_mask:0xf\n\t"
;                     "v_fmac_f32_e32 %5, %18, %17\n\t"
;                     "s_nop 0\n\t"
;                     "v_add_f32_dpp %0, %0, %0 row_half_mirror row_mask:0xf bank_mask:0xf\n\t"
;                     : "=&v"(sa), "=&v"(yy), "+v"(S0), "+v"(S1), "+v"(S2), "+v"(S3)
;                     : "v"(a.x), "v"(a.y), "v"(a.z), "v"(a.w), "v"(pr.x), "v"(pr.y), "v"(pr.z), "v"(pr.w), "v"(k.x), "v"(k.y), "v"(k.z), "v"(k.w), "v"(v));
;                 if (tl > 0) yb[(tl - 1) * SC_YS + lane] = yy;
;                 const f32x4 b_now = bb; pr = r;
;                 a = a1; bb = bb1; k = k1; r = r1; v = v1;
;                 if (tl + 2 < SC_TC) { const LAS float* sn = st + (tl + 2) * SC_STEP_F;
	v_pk_fma_f32 v[122:123], v[188:189], v[180:181], v[122:123] op_sel_hi:[0,1,1]
	v_pk_fma_f32 v[126:127], v[188:189], v[180:181], v[126:127] op_sel:[1,0,0] op_sel_hi:[1,1,1]
	v_add_f32_dpp v192, v192, v192 row_ror:4 row_mask:0xf bank_mask:0xf
	v_pk_fma_f32 v[124:125], v[188:189], v[182:183], v[124:125] op_sel_hi:[0,1,1]
	v_pk_fma_f32 v[128:129], v[188:189], v[182:183], v[128:129] op_sel:[1,0,0] op_sel_hi:[1,1,1]
	ds_write_b32 v204, v196 offset:4352
	v_add_f32_dpp v192, v192, v192 row_ror:8 row_mask:0xf bank_mask:0xf
	ds_write_b32 v206, v198 offset:4352
	ds_read_b128 v[152:155], v30 offset:19456
	ds_read_b128 v[156:159], v30 offset:19712
	ds_read_b128 v[160:163], v30 offset:19968
	ds_read_b128 v[164:167], v30 offset:20224
	ds_read_b32 v168, v31 offset:2432
	ds_read_b32 v169, v205 offset:2432
	v_mov_b32_dpp v194, v192 quad_perm:[1,0,3,2] row_mask:0xf bank_mask:0xf
	v_pk_fma_f32 v[122:123], v[192:193], v[176:177], v[122:123] op_sel_hi:[0,1,1]
	v_pk_fma_f32 v[126:127], v[194:195], v[176:177], v[126:127] op_sel_hi:[0,1,1]
	v_pk_fma_f32 v[124:125], v[192:193], v[178:179], v[124:125] op_sel_hi:[0,1,1]
	v_pk_fma_f32 v[128:129], v[194:195], v[178:179], v[128:129] op_sel_hi:[0,1,1]
	s_waitcnt lgkmcnt(13)
	v_pk_mul_f32 v[192:193], v[122:123], v[132:133]
	v_pk_mul_f32 v[194:195], v[126:127], v[132:133]
	v_pk_fma_f32 v[192:193], v[124:125], v[134:135], v[192:193]
	v_pk_fma_f32 v[194:195], v[128:129], v[134:135], v[194:195]
	v_add_f32_e32 v192, v192, v193
	v_add_f32_e32 v194, v194, v195
	v_pk_mul_f32 v[196:197], v[122:123], v[184:185]
	v_pk_mul_f32 v[198:199], v[126:127], v[184:185]
	v_pk_fma_f32 v[196:197], v[124:125], v[186:187], v[196:197]
	v_add_f32_dpp v192, v194, v192 quad_perm:[1,0,3,2] row_mask:0xf bank_mask:0xf
	v_pk_fma_f32 v[198:199], v[128:129], v[186:187], v[198:199]
	v_add_f32_e32 v196, v196, v197
	v_add_f32_e32 v198, v198, v199
	v_add_f32_dpp v192, v192, v192 quad_perm:[2,3,0,1] row_mask:0xf bank_mask:0xf
	s_waitcnt lgkmcnt(8)
	v_pk_fma_f32 v[122:123], v[148:149], v[140:141], v[122:123] op_sel_hi:[0,1,1]
	v_pk_fma_f32 v[126:127], v[148:149], v[140:141], v[126:127] op_sel:[1,0,0] op_sel_hi:[1,1,1]
	v_add_f32_dpp v192, v192, v192 row_ror:4 row_mask:0xf bank_mask:0xf
	v_pk_fma_f32 v[124:125], v[148:149], v[142:143], v[124:125] op_sel_hi:[0,1,1]
	v_pk_fma_f32 v[128:129], v[148:149], v[142:143], v[128:129] op_sel:[1,0,0] op_sel_hi:[1,1,1]
	ds_write_b32 v204, v196 offset:4624
	v_add_f32_dpp v192, v192, v192 row_ror:8 row_mask:0xf bank_mask:0xf
	ds_write_b32 v206, v198 offset:4624
	ds_read_b128 v[172:175], v30 offset:20480
	ds_read_b128 v[176:179], v30 offset:20736
	ds_read_b128 v[180:183], v30 offset:20992
	ds_read_b128 v[184:187], v30 offset:21248
	ds_read_b32 v188, v31 offset:2560
	ds_read_b32 v189, v205 offset:2560
	v_mov_b32_dpp v194, v192 quad_perm:[1,0,3,2] row_mask:0xf bank_mask:0xf
	v_pk_fma_f32 v[122:123], v[192:193], v[136:137], v[122:123] op_sel_hi:[0,1,1]
	v_pk_fma_f32 v[126:127], v[194:195], v[136:137], v[126:127] op_sel_hi:[0,1,1]
	v_pk_fma_f32 v[124:125], v[192:193], v[138:139], v[124:125] op_sel_hi:[0,1,1]
	v_pk_fma_f32 v[128:129], v[194:195], v[138:139], v[128:129] op_sel_hi:[0,1,1]
	s_waitcnt lgkmcnt(13)
	v_pk_mul_f32 v[192:193], v[122:123], v[152:153]
	v_pk_mul_f32 v[194:195], v[126:127], v[152:153]
	v_pk_fma_f32 v[192:193], v[124:125], v[154:155], v[192:193]
	v_pk_fma_f32 v[194:195], v[128:129], v[154:155], v[194:195]
	v_add_f32_e32 v192, v192, v193
	v_add_f32_e32 v194, v194, v195
	v_pk_mul_f32 v[196:197], v[122:123], v[144:145]
	v_pk_mul_f32 v[198:199], v[126:127], v[144:145]
	v_pk_fma_f32 v[196:197], v[124:125], v[146:147], v[196:197]
	v_add_f32_dpp v192, v194, v192 quad_perm:[1,0,3,2] row_mask:0xf bank_mask:0xf
	v_pk_fma_f32 v[198:199], v[128:129], v[146:147], v[198:199]
	v_add_f32_e32 v196, v196, v197
	v_add_f32_e32 v198, v198, v199
	v_add_f32_dpp v192, v192, v192 quad_perm:[2,3,0,1] row_mask:0xf bank_mask:0xf
	s_waitcnt lgkmcnt(8)
	v_pk_fma_f32 v[122:123], v[168:169], v[160:161], v[122:123] op_sel_hi:[0,1,1]
	v_pk_fma_f32 v[126:127], v[168:169], v[160:161], v[126:127] op_sel:[1,0,0] op_sel_hi:[1,1,1]
	v_add_f32_dpp v192, v192, v192 row_ror:4 row_mask:0xf bank_mask:0xf
	v_pk_fma_f32 v[124:125], v[168:169], v[162:163], v[124:125] op_sel_hi:[0,1,1]
	v_pk_fma_f32 v[128:129], v[168:169], v[162:163], v[128:129] op_sel:[1,0,0] op_sel_hi:[1,1,1]
	ds_write_b32 v204, v196 offset:4896
	v_add_f32_dpp v192, v192, v192 row_ror:8 row_mask:0xf bank_mask:0xf
	ds_write_b32 v206, v198 offset:4896
	ds_read_b128 v[132:135], v30 offset:21504
	ds_read_b128 v[136:139], v30 offset:21760
	ds_read_b128 v[140:143], v30 offset:22016
	ds_read_b128 v[144:147], v30 offset:22272
	ds_read_b32 v148, v31 offset:2688
	ds_read_b32 v149, v205 offset:2688
	v_mov_b32_dpp v194, v192 quad_perm:[1,0,3,2] row_mask:0xf bank_mask:0xf
	v_pk_fma_f32 v[122:123], v[192:193], v[156:157], v[122:123] op_sel_hi:[0,1,1]
	v_pk_fma_f32 v[126:127], v[194:195], v[156:157], v[126:127] op_sel_hi:[0,1,1]
	v_pk_fma_f32 v[124:125], v[192:193], v[158:159], v[124:125] op_sel_hi:[0,1,1]
	v_pk_fma_f32 v[128:129], v[194:195], v[158:159], v[128:129] op_sel_hi:[0,1,1]
	s_waitcnt lgkmcnt(13)
	v_pk_mul_f32 v[192:193], v[122:123], v[172:173]
	v_pk_mul_f32 v[194:195], v[126:127], v[172:173]
	v_pk_fma_f32 v[192:193], v[124:125], v[174:175], v[192:193]
	v_pk_fma_f32 v[194:195], v[128:129], v[174:175], v[194:195]
	v_add_f32_e32 v192, v192, v193
	v_add_f32_e32 v194, v194, v195
	v_pk_mul_f32 v[196:197], v[122:123], v[164:165]
	v_pk_mul_f32 v[198:199], v[126:127], v[164:165]
	v_pk_fma_f32 v[196:197], v[124:125], v[166:167], v[196:197]
	v_add_f32_dpp v192, v194, v192 quad_perm:[1,0,3,2] row_mask:0xf bank_mask:0xf
	v_pk_fma_f32 v[198:199], v[128:129], v[166:167], v[198:199]
	v_add_f32_e32 v196, v196, v197
	v_add_f32_e32 v198, v198, v199
	v_add_f32_dpp v192, v192, v192 quad_perm:[2,3,0,1] row_mask:0xf bank_mask:0xf
	s_waitcnt lgkmcnt(8)
; #define LAS __attribute__((address_space(3)))
; __device__ __forceinline__ void scan_unit(const Args& A, LAS unsigned char* lds, int s, int tid) {
;     ...
;             const LAS float* st = cur + 4 * jq; const LAS float* vp = cur + SC_V_OFF + rl;
;             f32x4 a = *(const LAS f32x4*)(st), bb = *(const LAS f32x4*)(st + 64), k = *(const LAS f32x4*)(st + 128), r = *(const LAS f32x4*)(st + 192);
;             float v = vp[0];
;             f32x4 a1 = *(const LAS f32x4*)(st + SC_STEP_F), bb1 = *(const LAS f32x4*)(st + SC_STEP_F + 64), k1 = *(const LAS f32x4*)(st + SC_STEP_F + 128), r1 = *(const LAS f32x4*)(st + SC_STEP_F + 192);
;             float v1 = vp[32];
;             f32x4 pr = (f32x4){0.f, 0.f, 0.f, 0.f};
; #pragma unroll
;             for (int tl = 0; tl < SC_TC; ++tl) {
;                 float sa, yy;
;                 asm volatile(
;                     "v_mul_f32_e32 %0, %2, %6\n\t"
;                     "v_mul_f32_e32 %1, %2, %10\n\t"
;                     "v_fmac_f32_e32 %0, %3, %7\n\t"
;                     "v_fmac_f32_e32 %1, %3, %11\n\t"
;                     "v_fmac_f32_e32 %0, %4, %8\n\t"
;                     "v_fmac_f32_e32 %1, %4, %12\n\t"
;                     "v_fmac_f32_e32 %0, %5, %9\n\t"
;                     "v_fmac_f32_e32 %1, %5, %13\n\t"
;                     "v_fmac_f32_e32 %2, %18, %14\n\t"
;                     "v_add_f32_dpp %0, %0, %0 quad_perm:[1,0,3,2] row_mask:0xf bank_mask:0xf\n\t"
;                     "v_fmac_f32_e32 %3, %18, %15\n\t"
;                     "v_fmac_f32_e32 %4, %18, %16\n\t"
;                     "v_add_f32_dpp %0, %0, %0 quad_perm:[2,3,0,1] row_mask:0xf bank_mask:0xf\n\t"
;                     "v_fmac_f32_e32 %5, %18, %17\n\t"
;                     "s_nop 0\n\t"
;                     "v_add_f32_dpp %0, %0, %0 row_half_mirror row_mask:0xf bank_mask:0xf\n\t"
;                     : "=&v"(sa), "=&v"(yy), "+v"(S0), "+v"(S1), "+v"(S2), "+v"(S3)
;                     : "v"(a.x), "v"(a.y), "v"(a.z), "v"(a.w), "v"(pr.x), "v"(pr.y), "v"(pr.z), "v"(pr.w), "v"(k.x), "v"(k.y), "v"(k.z), "v"(k.w), "v"(v));
;                 if (tl > 0) yb[(tl - 1) * SC_YS + lane] = yy;
;                 const f32x4 b_now = bb; pr = r;
;                 a = a1; bb = bb1; k = k1; r = r1; v = v1;
;                 if (tl + 2 < SC_TC) { const LAS float* sn = st + (tl + 2) * SC_STEP_F;
	v_pk_fma_f32 v[122:123], v[188:189], v[180:181], v[122:123] op_sel_hi:[0,1,1]
	v_pk_fma_f32 v[126:127], v[188:189], v[180:181], v[126:127] op_sel:[1,0,0] op_sel_hi:[1,1,1]
	v_add_f32_dpp v192, v192, v192 row_ror:4 row_mask:0xf bank_mask:0xf
	v_pk_fma_f32 v[124:125], v[188:189], v[182:183], v[124:125] op_sel_hi:[0,1,1]
	v_pk_fma_f32 v[128:129], v[188:189], v[182:183], v[128:129] op_sel:[1,0,0] op_sel_hi:[1,1,1]
	ds_write_b32 v204, v196 offset:5168
	v_add_f32_dpp v192, v192, v192 row_ror:8 row_mask:0xf bank_mask:0xf
	ds_write_b32 v206, v198 offset:5168
	ds_read_b128 v[152:155], v30 offset:22528
	ds_read_b128 v[156:159], v30 offset:22784
	ds_read_b128 v[160:163], v30 offset:23040
	ds_read_b128 v[164:167], v30 offset:23296
	ds_read_b32 v168, v31 offset:2816
	ds_read_b32 v169, v205 offset:2816
	v_mov_b32_dpp v194, v192 quad_perm:[1,0,3,2] row_mask:0xf bank_mask:0xf
	v_pk_fma_f32 v[122:123], v[192:193], v[176:177], v[122:123] op_sel_hi:[0,1,1]
	v_pk_fma_f32 v[126:127], v[194:195], v[176:177], v[126:127] op_sel_hi:[0,1,1]
	v_pk_fma_f32 v[124:125], v[192:193], v[178:179], v[124:125] op_sel_hi:[0,1,1]
	v_pk_fma_f32 v[128:129], v[194:195], v[178:179], v[128:129] op_sel_hi:[0,1,1]
	s_waitcnt lgkmcnt(13)
	v_pk_mul_f32 v[192:193], v[122:123], v[132:133]
	v_pk_mul_f32 v[194:195], v[126:127], v[132:133]
	v_pk_fma_f32 v[192:193], v[124:125], v[134:135], v[192:193]
	v_pk_fma_f32 v[194:195], v[128:129], v[134:135], v[194:195]
	v_add_f32_e32 v192, v192, v193
	v_add_f32_e32 v194, v194, v195
	v_pk_mul_f32 v[196:197], v[122:123], v[184:185]
	v_pk_mul_f32 v[198:199], v[126:127], v[184:185]
	v_pk_fma_f32 v[196:197], v[124:125], v[186:187], v[196:197]
	v_add_f32_dpp v192, v194, v192 quad_perm:[1,0,3,2] row_mask:0xf bank_mask:0xf
	v_pk_fma_f32 v[198:199], v[128:129], v[186:187], v[198:199]
	v_add_f32_e32 v196, v196, v197
	v_add_f32_e32 v198, v198, v199
	v_add_f32_dpp v192, v192, v192 quad_perm:[2,3,0,1] row_mask:0xf bank_mask:0xf
	s_waitcnt lgkmcnt(8)
	v_pk_fma_f32 v[122:123], v[148:149], v[140:141], v[122:123] op_sel_hi:[0,1,1]
	v_pk_fma_f32 v[126:127], v[148:149], v[140:141], v[126:127] op_sel:[1,0,0] op_sel_hi:[1,1,1]
	v_add_f32_dpp v192, v192, v192 row_ror:4 row_mask:0xf bank_mask:0xf
	v_pk_fma_f32 v[124:125], v[148:149], v[142:143], v[124:125] op_sel_hi:[0,1,1]
	v_pk_fma_f32 v[128:129], v[148:149], v[142:143], v[128:129] op_sel:[1,0,0] op_sel_hi:[1,1,1]
	ds_write_b32 v204, v196 offset:5440
	v_add_f32_dpp v192, v192, v192 row_ror:8 row_mask:0xf bank_mask:0xf
	ds_write_b32 v206, v198 offset:5440
	ds_read_b128 v[172:175], v30 offset:23552
	ds_read_b128 v[176:179], v30 offset:23808
	ds_read_b128 v[180:183], v30 offset:24064
	ds_read_b128 v[184:187], v30 offset:24320
	ds_read_b32 v188, v31 offset:2944
	ds_read_b32 v189, v205 offset:2944
	v_mov_b32_dpp v194, v192 quad_perm:[1,0,3,2] row_mask:0xf bank_mask:0xf
	v_pk_fma_f32 v[122:123], v[192:193], v[136:137], v[122:123] op_sel_hi:[0,1,1]
	v_pk_fma_f32 v[126:127], v[194:195], v[136:137], v[126:127] op_sel_hi:[0,1,1]
	v_pk_fma_f32 v[124:125], v[192:193], v[138:139], v[124:125] op_sel_hi:[0,1,1]
	v_pk_fma_f32 v[128:129], v[194:195], v[138:139], v[128:129] op_sel_hi:[0,1,1]
	s_waitcnt lgkmcnt(13)
	v_pk_mul_f32 v[192:193], v[122:123], v[152:153]
	v_pk_mul_f32 v[194:195], v[126:127], v[152:153]
	v_pk_fma_f32 v[192:193], v[124:125], v[154:155], v[192:193]
	v_pk_fma_f32 v[194:195], v[128:129], v[154:155], v[194:195]
	v_add_f32_e32 v192, v192, v193
	v_add_f32_e32 v194, v194, v195
	v_pk_mul_f32 v[196:197], v[122:123], v[144:145]
	v_pk_mul_f32 v[198:199], v[126:127], v[144:145]
	v_pk_fma_f32 v[196:197], v[124:125], v[146:147], v[196:197]
	v_add_f32_dpp v192, v194, v192 quad_perm:[1,0,3,2] row_mask:0xf bank_mask:0xf
	v_pk_fma_f32 v[198:199], v[128:129], v[146:147], v[198:199]
	v_add_f32_e32 v196, v196, v197
	v_add_f32_e32 v198, v198, v199
	v_add_f32_dpp v192, v192, v192 quad_perm:[2,3,0,1] row_mask:0xf bank_mask:0xf
	s_waitcnt lgkmcnt(8)
	v_pk_fma_f32 v[122:123], v[168:169], v[160:161], v[122:123] op_sel_hi:[0,1,1]
	v_pk_fma_f32 v[126:127], v[168:169], v[160:161], v[126:127] op_sel:[1,0,0] op_sel_hi:[1,1,1]
	v_add_f32_dpp v192, v192, v192 row_ror:4 row_mask:0xf bank_mask:0xf
	v_pk_fma_f32 v[124:125], v[168:169], v[162:163], v[124:125] op_sel_hi:[0,1,1]
	v_pk_fma_f32 v[128:129], v[168:169], v[162:163], v[128:129] op_sel:[1,0,0] op_sel_hi:[1,1,1]
	ds_write_b32 v204, v196 offset:5712
	v_add_f32_dpp v192, v192, v192 row_ror:8 row_mask:0xf bank_mask:0xf
	ds_write_b32 v206, v198 offset:5712
	ds_read_b128 v[132:135], v30 offset:24576
	ds_read_b128 v[136:139], v30 offset:24832
	ds_read_b128 v[140:143], v30 offset:25088
	ds_read_b128 v[144:147], v30 offset:25344
	ds_read_b32 v148, v31 offset:3072
	ds_read_b32 v149, v205 offset:3072
	v_mov_b32_dpp v194, v192 quad_perm:[1,0,3,2] row_mask:0xf bank_mask:0xf
	v_pk_fma_f32 v[122:123], v[192:193], v[156:157], v[122:123] op_sel_hi:[0,1,1]
	v_pk_fma_f32 v[126:127], v[194:195], v[156:157], v[126:127] op_sel_hi:[0,1,1]
	v_pk_fma_f32 v[124:125], v[192:193], v[158:159], v[124:125] op_sel_hi:[0,1,1]
	v_pk_fma_f32 v[128:129], v[194:195], v[158:159], v[128:129] op_sel_hi:[0,1,1]
	s_waitcnt lgkmcnt(13)
	v_pk_mul_f32 v[192:193], v[122:123], v[172:173]
	v_pk_mul_f32 v[194:195], v[126:127], v[172:173]
	v_pk_fma_f32 v[192:193], v[124:125], v[174:175], v[192:193]
	v_pk_fma_f32 v[194:195], v[128:129], v[174:175], v[194:195]
	v_add_f32_e32 v192, v192, v193
	v_add_f32_e32 v194, v194, v195
	v_pk_mul_f32 v[196:197], v[122:123], v[164:165]
	v_pk_mul_f32 v[198:199], v[126:127], v[164:165]
	v_pk_fma_f32 v[196:197], v[124:125], v[166:167], v[196:197]
	v_add_f32_dpp v192, v194, v192 quad_perm:[1,0,3,2] row_mask:0xf bank_mask:0xf
	v_pk_fma_f32 v[198:199], v[128:129], v[166:167], v[198:199]
	v_add_f32_e32 v196, v196, v197
	v_add_f32_e32 v198, v198, v199
	v_add_f32_dpp v192, v192, v192 quad_perm:[2,3,0,1] row_mask:0xf bank_mask:0xf
	s_waitcnt lgkmcnt(8)
; #define LAS __attribute__((address_space(3)))
; __device__ __forceinline__ void scan_unit(const Args& A, LAS unsigned char* lds, int s, int tid) {
;     ...
;             const LAS float* st = cur + 4 * jq; const LAS float* vp = cur + SC_V_OFF + rl;
;             f32x4 a = *(const LAS f32x4*)(st), bb = *(const LAS f32x4*)(st + 64), k = *(const LAS f32x4*)(st + 128), r = *(const LAS f32x4*)(st + 192);
;             float v = vp[0];
;             f32x4 a1 = *(const LAS f32x4*)(st + SC_STEP_F), bb1 = *(const LAS f32x4*)(st + SC_STEP_F + 64), k1 = *(const LAS f32x4*)(st + SC_STEP_F + 128), r1 = *(const LAS f32x4*)(st + SC_STEP_F + 192);
;             float v1 = vp[32];
;             f32x4 pr = (f32x4){0.f, 0.f, 0.f, 0.f};
; #pragma unroll
;             for (int tl = 0; tl < SC_TC; ++tl) {
;                 float sa, yy;
;                 asm volatile(
;                     "v_mul_f32_e32 %0, %2, %6\n\t"
;                     "v_mul_f32_e32 %1, %2, %10\n\t"
;                     "v_fmac_f32_e32 %0, %3, %7\n\t"
;                     "v_fmac_f32_e32 %1, %3, %11\n\t"
;                     "v_fmac_f32_e32 %0, %4, %8\n\t"
;                     "v_fmac_f32_e32 %1, %4, %12\n\t"
;                     "v_fmac_f32_e32 %0, %5, %9\n\t"
;                     "v_fmac_f32_e32 %1, %5, %13\n\t"
;                     "v_fmac_f32_e32 %2, %18, %14\n\t"
;                     "v_add_f32_dpp %0, %0, %0 quad_perm:[1,0,3,2] row_mask:0xf bank_mask:0xf\n\t"
;                     "v_fmac_f32_e32 %3, %18, %15\n\t"
;                     "v_fmac_f32_e32 %4, %18, %16\n\t"
;                     "v_add_f32_dpp %0, %0, %0 quad_perm:[2,3,0,1] row_mask:0xf bank_mask:0xf\n\t"
;                     "v_fmac_f32_e32 %5, %18, %17\n\t"
;                     "s_nop 0\n\t"
;                     "v_add_f32_dpp %0, %0, %0 row_half_mirror row_mask:0xf bank_mask:0xf\n\t"
;                     : "=&v"(sa), "=&v"(yy), "+v"(S0), "+v"(S1), "+v"(S2), "+v"(S3)
;                     : "v"(a.x), "v"(a.y), "v"(a.z), "v"(a.w), "v"(pr.x), "v"(pr.y), "v"(pr.z), "v"(pr.w), "v"(k.x), "v"(k.y), "v"(k.z), "v"(k.w), "v"(v));
;                 if (tl > 0) yb[(tl - 1) * SC_YS + lane] = yy;
;                 const f32x4 b_now = bb; pr = r;
;                 a = a1; bb = bb1; k = k1; r = r1; v = v1;
;                 if (tl + 2 < SC_TC) { const LAS float* sn = st + (tl + 2) * SC_STEP_F;
	v_pk_fma_f32 v[122:123], v[188:189], v[180:181], v[122:123] op_sel_hi:[0,1,1]
	v_pk_fma_f32 v[126:127], v[188:189], v[180:181], v[126:127] op_sel:[1,0,0] op_sel_hi:[1,1,1]
	v_add_f32_dpp v192, v192, v192 row_ror:4 row_mask:0xf bank_mask:0xf
	v_pk_fma_f32 v[124:125], v[188:189], v[182:183], v[124:125] op_sel_hi:[0,1,1]
	v_pk_fma_f32 v[128:129], v[188:189], v[182:183], v[128:129] op_sel:[1,0,0] op_sel_hi:[1,1,1]
	ds_write_b32 v204, v196 offset:5984
	v_add_f32_dpp v192, v192, v192 row_ror:8 row_mask:0xf bank_mask:0xf
	ds_write_b32 v206, v198 offset:5984
	ds_read_b128 v[152:155], v30 offset:25600
	ds_read_b128 v[156:159], v30 offset:25856
	ds_read_b128 v[160:163], v30 offset:26112
	ds_read_b128 v[164:167], v30 offset:26368
	ds_read_b32 v168, v31 offset:3200
	ds_read_b32 v169, v205 offset:3200
	v_mov_b32_dpp v194, v192 quad_perm:[1,0,3,2] row_mask:0xf bank_mask:0xf
	v_pk_fma_f32 v[122:123], v[192:193], v[176:177], v[122:123] op_sel_hi:[0,1,1]
	v_pk_fma_f32 v[126:127], v[194:195], v[176:177], v[126:127] op_sel_hi:[0,1,1]
	v_pk_fma_f32 v[124:125], v[192:193], v[178:179], v[124:125] op_sel_hi:[0,1,1]
	v_pk_fma_f32 v[128:129], v[194:195], v[178:179], v[128:129] op_sel_hi:[0,1,1]
	s_waitcnt lgkmcnt(13)
	v_pk_mul_f32 v[192:193], v[122:123], v[132:133]
	v_pk_mul_f32 v[194:195], v[126:127], v[132:133]
	v_pk_fma_f32 v[192:193], v[124:125], v[134:135], v[192:193]
	v_pk_fma_f32 v[194:195], v[128:129], v[134:135], v[194:195]
	v_add_f32_e32 v192, v192, v193
	v_add_f32_e32 v194, v194, v195
	v_pk_mul_f32 v[196:197], v[122:123], v[184:185]
	v_pk_mul_f32 v[198:199], v[126:127], v[184:185]
	v_pk_fma_f32 v[196:197], v[124:125], v[186:187], v[196:197]
	v_add_f32_dpp v192, v194, v192 quad_perm:[1,0,3,2] row_mask:0xf bank_mask:0xf
	v_pk_fma_f32 v[198:199], v[128:129], v[186:187], v[198:199]
	v_add_f32_e32 v196, v196, v197
	v_add_f32_e32 v198, v198, v199
	v_add_f32_dpp v192, v192, v192 quad_perm:[2,3,0,1] row_mask:0xf bank_mask:0xf
	s_waitcnt lgkmcnt(8)
	v_pk_fma_f32 v[122:123], v[148:149], v[140:141], v[122:123] op_sel_hi:[0,1,1]
	v_pk_fma_f32 v[126:127], v[148:149], v[140:141], v[126:127] op_sel:[1,0,0] op_sel_hi:[1,1,1]
	v_add_f32_dpp v192, v192, v192 row_ror:4 row_mask:0xf bank_mask:0xf
	v_pk_fma_f32 v[124:125], v[148:149], v[142:143], v[124:125] op_sel_hi:[0,1,1]
	v_pk_fma_f32 v[128:129], v[148:149], v[142:143], v[128:129] op_sel:[1,0,0] op_sel_hi:[1,1,1]
	ds_write_b32 v204, v196 offset:6256
	v_add_f32_dpp v192, v192, v192 row_ror:8 row_mask:0xf bank_mask:0xf
	ds_write_b32 v206, v198 offset:6256
	ds_read_b128 v[172:175], v30 offset:26624
	ds_read_b128 v[176:179], v30 offset:26880
	ds_read_b128 v[180:183], v30 offset:27136
	ds_read_b128 v[184:187], v30 offset:27392
	ds_read_b32 v188, v31 offset:3328
	ds_read_b32 v189, v205 offset:3328
	v_mov_b32_dpp v194, v192 quad_perm:[1,0,3,2] row_mask:0xf bank_mask:0xf
	v_pk_fma_f32 v[122:123], v[192:193], v[136:137], v[122:123] op_sel_hi:[0,1,1]
	v_pk_fma_f32 v[126:127], v[194:195], v[136:137], v[126:127] op_sel_hi:[0,1,1]
	v_pk_fma_f32 v[124:125], v[192:193], v[138:139], v[124:125] op_sel_hi:[0,1,1]
	v_pk_fma_f32 v[128:129], v[194:195], v[138:139], v[128:129] op_sel_hi:[0,1,1]
	s_waitcnt lgkmcnt(13)
	v_pk_mul_f32 v[192:193], v[122:123], v[152:153]
	v_pk_mul_f32 v[194:195], v[126:127], v[152:153]
	v_pk_fma_f32 v[192:193], v[124:125], v[154:155], v[192:193]
	v_pk_fma_f32 v[194:195], v[128:129], v[154:155], v[194:195]
	v_add_f32_e32 v192, v192, v193
	v_add_f32_e32 v194, v194, v195
	v_pk_mul_f32 v[196:197], v[122:123], v[144:145]
	v_pk_mul_f32 v[198:199], v[126:127], v[144:145]
	v_pk_fma_f32 v[196:197], v[124:125], v[146:147], v[196:197]
	v_add_f32_dpp v192, v194, v192 quad_perm:[1,0,3,2] row_mask:0xf bank_mask:0xf
	v_pk_fma_f32 v[198:199], v[128:129], v[146:147], v[198:199]
	v_add_f32_e32 v196, v196, v197
	v_add_f32_e32 v198, v198, v199
	v_add_f32_dpp v192, v192, v192 quad_perm:[2,3,0,1] row_mask:0xf bank_mask:0xf
	s_waitcnt lgkmcnt(8)
	v_pk_fma_f32 v[122:123], v[168:169], v[160:161], v[122:123] op_sel_hi:[0,1,1]
	v_pk_fma_f32 v[126:127], v[168:169], v[160:161], v[126:127] op_sel:[1,0,0] op_sel_hi:[1,1,1]
	v_add_f32_dpp v192, v192, v192 row_ror:4 row_mask:0xf bank_mask:0xf
	v_pk_fma_f32 v[124:125], v[168:169], v[162:163], v[124:125] op_sel_hi:[0,1,1]
	v_pk_fma_f32 v[128:129], v[168:169], v[162:163], v[128:129] op_sel:[1,0,0] op_sel_hi:[1,1,1]
	ds_write_b32 v204, v196 offset:6528
	v_add_f32_dpp v192, v192, v192 row_ror:8 row_mask:0xf bank_mask:0xf
	ds_write_b32 v206, v198 offset:6528
	ds_read_b128 v[132:135], v30 offset:27648
	ds_read_b128 v[136:139], v30 offset:27904
	ds_read_b128 v[140:143], v30 offset:28160
	ds_read_b128 v[144:147], v30 offset:28416
	ds_read_b32 v148, v31 offset:3456
	ds_read_b32 v149, v205 offset:3456
	v_mov_b32_dpp v194, v192 quad_perm:[1,0,3,2] row_mask:0xf bank_mask:0xf
	v_pk_fma_f32 v[122:123], v[192:193], v[156:157], v[122:123] op_sel_hi:[0,1,1]
	v_pk_fma_f32 v[126:127], v[194:195], v[156:157], v[126:127] op_sel_hi:[0,1,1]
	v_pk_fma_f32 v[124:125], v[192:193], v[158:159], v[124:125] op_sel_hi:[0,1,1]
	v_pk_fma_f32 v[128:129], v[194:195], v[158:159], v[128:129] op_sel_hi:[0,1,1]
	s_waitcnt lgkmcnt(13)
	v_pk_mul_f32 v[192:193], v[122:123], v[172:173]
	v_pk_mul_f32 v[194:195], v[126:127], v[172:173]
	v_pk_fma_f32 v[192:193], v[124:125], v[174:175], v[192:193]
	v_pk_fma_f32 v[194:195], v[128:129], v[174:175], v[194:195]
	v_add_f32_e32 v192, v192, v193
	v_add_f32_e32 v194, v194, v195
	v_pk_mul_f32 v[196:197], v[122:123], v[164:165]
	v_pk_mul_f32 v[198:199], v[126:127], v[164:165]
	v_pk_fma_f32 v[196:197], v[124:125], v[166:167], v[196:197]
	v_add_f32_dpp v192, v194, v192 quad_perm:[1,0,3,2] row_mask:0xf bank_mask:0xf
	v_pk_fma_f32 v[198:199], v[128:129], v[166:167], v[198:199]
	v_add_f32_e32 v196, v196, v197
	v_add_f32_e32 v198, v198, v199
	v_add_f32_dpp v192, v192, v192 quad_perm:[2,3,0,1] row_mask:0xf bank_mask:0xf
	s_waitcnt lgkmcnt(8)
; #define LAS __attribute__((address_space(3)))
; __device__ __forceinline__ void scan_unit(const Args& A, LAS unsigned char* lds, int s, int tid) {
;     ...
;             const LAS float* st = cur + 4 * jq; const LAS float* vp = cur + SC_V_OFF + rl;
;             f32x4 a = *(const LAS f32x4*)(st), bb = *(const LAS f32x4*)(st + 64), k = *(const LAS f32x4*)(st + 128), r = *(const LAS f32x4*)(st + 192);
;             float v = vp[0];
;             f32x4 a1 = *(const LAS f32x4*)(st + SC_STEP_F), bb1 = *(const LAS f32x4*)(st + SC_STEP_F + 64), k1 = *(const LAS f32x4*)(st + SC_STEP_F + 128), r1 = *(const LAS f32x4*)(st + SC_STEP_F + 192);
;             float v1 = vp[32];
;             f32x4 pr = (f32x4){0.f, 0.f, 0.f, 0.f};
; #pragma unroll
;             for (int tl = 0; tl < SC_TC; ++tl) {
;                 float sa, yy;
;                 asm volatile(
;                     "v_mul_f32_e32 %0, %2, %6\n\t"
;                     "v_mul_f32_e32 %1, %2, %10\n\t"
;                     "v_fmac_f32_e32 %0, %3, %7\n\t"
;                     "v_fmac_f32_e32 %1, %3, %11\n\t"
;                     "v_fmac_f32_e32 %0, %4, %8\n\t"
;                     "v_fmac_f32_e32 %1, %4, %12\n\t"
;                     "v_fmac_f32_e32 %0, %5, %9\n\t"
;                     "v_fmac_f32_e32 %1, %5, %13\n\t"
;                     "v_fmac_f32_e32 %2, %18, %14\n\t"
;                     "v_add_f32_dpp %0, %0, %0 quad_perm:[1,0,3,2] row_mask:0xf bank_mask:0xf\n\t"
;                     "v_fmac_f32_e32 %3, %18, %15\n\t"
;                     "v_fmac_f32_e32 %4, %18, %16\n\t"
;                     "v_add_f32_dpp %0, %0, %0 quad_perm:[2,3,0,1] row_mask:0xf bank_mask:0xf\n\t"
;                     "v_fmac_f32_e32 %5, %18, %17\n\t"
;                     "s_nop 0\n\t"
;                     "v_add_f32_dpp %0, %0, %0 row_half_mirror row_mask:0xf bank_mask:0xf\n\t"
;                     : "=&v"(sa), "=&v"(yy), "+v"(S0), "+v"(S1), "+v"(S2), "+v"(S3)
;                     : "v"(a.x), "v"(a.y), "v"(a.z), "v"(a.w), "v"(pr.x), "v"(pr.y), "v"(pr.z), "v"(pr.w), "v"(k.x), "v"(k.y), "v"(k.z), "v"(k.w), "v"(v));
;                 if (tl > 0) yb[(tl - 1) * SC_YS + lane] = yy;
;                 const f32x4 b_now = bb; pr = r;
;                 a = a1; bb = bb1; k = k1; r = r1; v = v1;
;                 if (tl + 2 < SC_TC) { const LAS float* sn = st + (tl + 2) * SC_STEP_F;
	v_pk_fma_f32 v[122:123], v[188:189], v[180:181], v[122:123] op_sel_hi:[0,1,1]
	v_pk_fma_f32 v[126:127], v[188:189], v[180:181], v[126:127] op_sel:[1,0,0] op_sel_hi:[1,1,1]
	v_add_f32_dpp v192, v192, v192 row_ror:4 row_mask:0xf bank_mask:0xf
	v_pk_fma_f32 v[124:125], v[188:189], v[182:183], v[124:125] op_sel_hi:[0,1,1]
	v_pk_fma_f32 v[128:129], v[188:189], v[182:183], v[128:129] op_sel:[1,0,0] op_sel_hi:[1,1,1]
	ds_write_b32 v204, v196 offset:6800
	v_add_f32_dpp v192, v192, v192 row_ror:8 row_mask:0xf bank_mask:0xf
	ds_write_b32 v206, v198 offset:6800
	ds_read_b128 v[152:155], v30 offset:28672
	ds_read_b128 v[156:159], v30 offset:28928
	ds_read_b128 v[160:163], v30 offset:29184
	ds_read_b128 v[164:167], v30 offset:29440
	ds_read_b32 v168, v31 offset:3584
	ds_read_b32 v169, v205 offset:3584
	v_mov_b32_dpp v194, v192 quad_perm:[1,0,3,2] row_mask:0xf bank_mask:0xf
	v_pk_fma_f32 v[122:123], v[192:193], v[176:177], v[122:123] op_sel_hi:[0,1,1]
	v_pk_fma_f32 v[126:127], v[194:195], v[176:177], v[126:127] op_sel_hi:[0,1,1]
	v_pk_fma_f32 v[124:125], v[192:193], v[178:179], v[124:125] op_sel_hi:[0,1,1]
	v_pk_fma_f32 v[128:129], v[194:195], v[178:179], v[128:129] op_sel_hi:[0,1,1]
	s_waitcnt lgkmcnt(13)
	v_pk_mul_f32 v[192:193], v[122:123], v[132:133]
	v_pk_mul_f32 v[194:195], v[126:127], v[132:133]
	v_pk_fma_f32 v[192:193], v[124:125], v[134:135], v[192:193]
	v_pk_fma_f32 v[194:195], v[128:129], v[134:135], v[194:195]
	v_add_f32_e32 v192, v192, v193
	v_add_f32_e32 v194, v194, v195
	v_pk_mul_f32 v[196:197], v[122:123], v[184:185]
	v_pk_mul_f32 v[198:199], v[126:127], v[184:185]
	v_pk_fma_f32 v[196:197], v[124:125], v[186:187], v[196:197]
	v_add_f32_dpp v192, v194, v192 quad_perm:[1,0,3,2] row_mask:0xf bank_mask:0xf
	v_pk_fma_f32 v[198:199], v[128:129], v[186:187], v[198:199]
	v_add_f32_e32 v196, v196, v197
	v_add_f32_e32 v198, v198, v199
	v_add_f32_dpp v192, v192, v192 quad_perm:[2,3,0,1] row_mask:0xf bank_mask:0xf
	s_waitcnt lgkmcnt(8)
	v_pk_fma_f32 v[122:123], v[148:149], v[140:141], v[122:123] op_sel_hi:[0,1,1]
	v_pk_fma_f32 v[126:127], v[148:149], v[140:141], v[126:127] op_sel:[1,0,0] op_sel_hi:[1,1,1]
	v_add_f32_dpp v192, v192, v192 row_ror:4 row_mask:0xf bank_mask:0xf
	v_pk_fma_f32 v[124:125], v[148:149], v[142:143], v[124:125] op_sel_hi:[0,1,1]
	v_pk_fma_f32 v[128:129], v[148:149], v[142:143], v[128:129] op_sel:[1,0,0] op_sel_hi:[1,1,1]
	ds_write_b32 v204, v196 offset:7072
	v_add_f32_dpp v192, v192, v192 row_ror:8 row_mask:0xf bank_mask:0xf
	ds_write_b32 v206, v198 offset:7072
	ds_read_b128 v[172:175], v30 offset:29696
	ds_read_b128 v[176:179], v30 offset:29952
	ds_read_b128 v[180:183], v30 offset:30208
	ds_read_b128 v[184:187], v30 offset:30464
	ds_read_b32 v188, v31 offset:3712
	ds_read_b32 v189, v205 offset:3712
	v_mov_b32_dpp v194, v192 quad_perm:[1,0,3,2] row_mask:0xf bank_mask:0xf
	v_pk_fma_f32 v[122:123], v[192:193], v[136:137], v[122:123] op_sel_hi:[0,1,1]
	v_pk_fma_f32 v[126:127], v[194:195], v[136:137], v[126:127] op_sel_hi:[0,1,1]
	v_pk_fma_f32 v[124:125], v[192:193], v[138:139], v[124:125] op_sel_hi:[0,1,1]
	v_pk_fma_f32 v[128:129], v[194:195], v[138:139], v[128:129] op_sel_hi:[0,1,1]
	s_waitcnt lgkmcnt(13)
	v_pk_mul_f32 v[192:193], v[122:123], v[152:153]
	v_pk_mul_f32 v[194:195], v[126:127], v[152:153]
	v_pk_fma_f32 v[192:193], v[124:125], v[154:155], v[192:193]
	v_pk_fma_f32 v[194:195], v[128:129], v[154:155], v[194:195]
	v_add_f32_e32 v192, v192, v193
	v_add_f32_e32 v194, v194, v195
	v_pk_mul_f32 v[196:197], v[122:123], v[144:145]
	v_pk_mul_f32 v[198:199], v[126:127], v[144:145]
	v_pk_fma_f32 v[196:197], v[124:125], v[146:147], v[196:197]
	v_add_f32_dpp v192, v194, v192 quad_perm:[1,0,3,2] row_mask:0xf bank_mask:0xf
	v_pk_fma_f32 v[198:199], v[128:129], v[146:147], v[198:199]
	v_add_f32_e32 v196, v196, v197
	v_add_f32_e32 v198, v198, v199
	v_add_f32_dpp v192, v192, v192 quad_perm:[2,3,0,1] row_mask:0xf bank_mask:0xf
	s_waitcnt lgkmcnt(8)
	v_pk_fma_f32 v[122:123], v[168:169], v[160:161], v[122:123] op_sel_hi:[0,1,1]
	v_pk_fma_f32 v[126:127], v[168:169], v[160:161], v[126:127] op_sel:[1,0,0] op_sel_hi:[1,1,1]
	v_add_f32_dpp v192, v192, v192 row_ror:4 row_mask:0xf bank_mask:0xf
	v_pk_fma_f32 v[124:125], v[168:169], v[162:163], v[124:125] op_sel_hi:[0,1,1]
	v_pk_fma_f32 v[128:129], v[168:169], v[162:163], v[128:129] op_sel:[1,0,0] op_sel_hi:[1,1,1]
	ds_write_b32 v204, v196 offset:7344
	v_add_f32_dpp v192, v192, v192 row_ror:8 row_mask:0xf bank_mask:0xf
	ds_write_b32 v206, v198 offset:7344
	ds_read_b128 v[132:135], v30 offset:30720
	ds_read_b128 v[136:139], v30 offset:30976
	ds_read_b128 v[140:143], v30 offset:31232
	ds_read_b128 v[144:147], v30 offset:31488
	ds_read_b32 v148, v31 offset:3840
	ds_read_b32 v149, v205 offset:3840
	v_mov_b32_dpp v194, v192 quad_perm:[1,0,3,2] row_mask:0xf bank_mask:0xf
	v_pk_fma_f32 v[122:123], v[192:193], v[156:157], v[122:123] op_sel_hi:[0,1,1]
	v_pk_fma_f32 v[126:127], v[194:195], v[156:157], v[126:127] op_sel_hi:[0,1,1]
	v_pk_fma_f32 v[124:125], v[192:193], v[158:159], v[124:125] op_sel_hi:[0,1,1]
	v_pk_fma_f32 v[128:129], v[194:195], v[158:159], v[128:129] op_sel_hi:[0,1,1]
	s_waitcnt lgkmcnt(13)
	v_pk_mul_f32 v[192:193], v[122:123], v[172:173]
	v_pk_mul_f32 v[194:195], v[126:127], v[172:173]
	v_pk_fma_f32 v[192:193], v[124:125], v[174:175], v[192:193]
	v_pk_fma_f32 v[194:195], v[128:129], v[174:175], v[194:195]
	v_add_f32_e32 v192, v192, v193
	v_add_f32_e32 v194, v194, v195
	v_pk_mul_f32 v[196:197], v[122:123], v[164:165]
	v_pk_mul_f32 v[198:199], v[126:127], v[164:165]
	v_pk_fma_f32 v[196:197], v[124:125], v[166:167], v[196:197]
	v_add_f32_dpp v192, v194, v192 quad_perm:[1,0,3,2] row_mask:0xf bank_mask:0xf
	v_pk_fma_f32 v[198:199], v[128:129], v[166:167], v[198:199]
	v_add_f32_e32 v196, v196, v197
	v_add_f32_e32 v198, v198, v199
	v_add_f32_dpp v192, v192, v192 quad_perm:[2,3,0,1] row_mask:0xf bank_mask:0xf
	s_waitcnt lgkmcnt(8)
; #define LAS __attribute__((address_space(3)))
; __device__ __forceinline__ float sc_fma(float a, float b, float c) { float r; asm("v_fma_f32 %0, %1, %2, %3" : "=v"(r) : "v"(a), "v"(b), "v"(c)); return r; }
; __device__ __forceinline__ float sc_mul(float a, float b) { float r; asm("v_mul_f32_e32 %0, %1, %2" : "=v"(r) : "v"(a), "v"(b)); return r; }
; __device__ __forceinline__ void scan_unit(const Args& A, LAS unsigned char* lds, int s, int tid) {
;     ...
;                 if (tl + 2 < SC_TC) { const LAS float* sn = st + (tl + 2) * SC_STEP_F;
;                     a1 = *(const LAS f32x4*)(sn); bb1 = *(const LAS f32x4*)(sn + 64); k1 = *(const LAS f32x4*)(sn + 128); r1 = *(const LAS f32x4*)(sn + 192); v1 = vp[(tl + 2) * 32]; }
;                 __builtin_amdgcn_sched_barrier(0);
;                 if (tl + 2 >= SC_TC) asm volatile("s_nop 1");
;                 asm volatile(
;                     "v_add_f32_dpp %4, %4, %4 row_mirror row_mask:0xf bank_mask:0xf\n\t"
;                     "v_fmac_f32_e32 %0, %4, %5\n\t"
;                     "v_fmac_f32_e32 %1, %4, %6\n\t"
;                     "v_fmac_f32_e32 %2, %4, %7\n\t"
;                     "v_fmac_f32_e32 %3, %4, %8\n\t"
;                     : "+v"(S0), "+v"(S1), "+v"(S2), "+v"(S3), "+v"(sa)
;                     : "v"(b_now.x), "v"(b_now.y), "v"(b_now.z), "v"(b_now.w));
;             }
;             { float yy = sc_mul(S0, pr.x); yy = sc_fma(S1, pr.y, yy); yy = sc_fma(S2, pr.z, yy); yy = sc_fma(S3, pr.w, yy); yb[(SC_TC - 1) * SC_YS + lane] = yy; }
;             { const f32x4 ge = *(const LAS f32x4*)(cur + SC_G_OFF + 4 * jq); S0 = sc_mul(S0, ge.x); S1 = sc_mul(S1, ge.y); S2 = sc_mul(S2, ge.z); S3 = sc_mul(S3, ge.w); }
	v_pk_fma_f32 v[122:123], v[188:189], v[180:181], v[122:123] op_sel_hi:[0,1,1]
	v_pk_fma_f32 v[126:127], v[188:189], v[180:181], v[126:127] op_sel:[1,0,0] op_sel_hi:[1,1,1]
	v_add_f32_dpp v192, v192, v192 row_ror:4 row_mask:0xf bank_mask:0xf
	v_pk_fma_f32 v[124:125], v[188:189], v[182:183], v[124:125] op_sel_hi:[0,1,1]
	v_pk_fma_f32 v[128:129], v[188:189], v[182:183], v[128:129] op_sel:[1,0,0] op_sel_hi:[1,1,1]
	ds_write_b32 v204, v196 offset:7616
	v_add_f32_dpp v192, v192, v192 row_ror:8 row_mask:0xf bank_mask:0xf
	ds_write_b32 v206, v198 offset:7616
	ds_read_b128 v[152:155], v30 offset:31744
	ds_read_b128 v[156:159], v30 offset:32000
	ds_read_b128 v[160:163], v30 offset:32256
	ds_read_b128 v[164:167], v30 offset:32512
	ds_read_b32 v168, v31 offset:3968
	ds_read_b32 v169, v205 offset:3968
	v_mov_b32_dpp v194, v192 quad_perm:[1,0,3,2] row_mask:0xf bank_mask:0xf
	v_pk_fma_f32 v[122:123], v[192:193], v[176:177], v[122:123] op_sel_hi:[0,1,1]
	v_pk_fma_f32 v[126:127], v[194:195], v[176:177], v[126:127] op_sel_hi:[0,1,1]
	v_pk_fma_f32 v[124:125], v[192:193], v[178:179], v[124:125] op_sel_hi:[0,1,1]
	v_pk_fma_f32 v[128:129], v[194:195], v[178:179], v[128:129] op_sel_hi:[0,1,1]
	s_waitcnt lgkmcnt(13)
	v_pk_mul_f32 v[192:193], v[122:123], v[132:133]
	v_pk_mul_f32 v[194:195], v[126:127], v[132:133]
	v_pk_fma_f32 v[192:193], v[124:125], v[134:135], v[192:193]
	v_pk_fma_f32 v[194:195], v[128:129], v[134:135], v[194:195]
	v_add_f32_e32 v192, v192, v193
	v_add_f32_e32 v194, v194, v195
	v_pk_mul_f32 v[196:197], v[122:123], v[184:185]
	v_pk_mul_f32 v[198:199], v[126:127], v[184:185]
	v_pk_fma_f32 v[196:197], v[124:125], v[186:187], v[196:197]
	v_add_f32_dpp v192, v194, v192 quad_perm:[1,0,3,2] row_mask:0xf bank_mask:0xf
	v_pk_fma_f32 v[198:199], v[128:129], v[186:187], v[198:199]
	v_add_f32_e32 v196, v196, v197
	v_add_f32_dpp v192, v192, v192 quad_perm:[2,3,0,1] row_mask:0xf bank_mask:0xf
	v_add_f32_e32 v198, v198, v199
	s_waitcnt lgkmcnt(8)
	v_add_f32_dpp v192, v192, v192 row_ror:4 row_mask:0xf bank_mask:0xf
	v_pk_fma_f32 v[122:123], v[148:149], v[140:141], v[122:123] op_sel_hi:[0,1,1]
	v_pk_fma_f32 v[126:127], v[148:149], v[140:141], v[126:127] op_sel:[1,0,0] op_sel_hi:[1,1,1]
	v_pk_fma_f32 v[124:125], v[148:149], v[142:143], v[124:125] op_sel_hi:[0,1,1]
	v_add_f32_dpp v192, v192, v192 row_ror:8 row_mask:0xf bank_mask:0xf
	v_pk_fma_f32 v[128:129], v[148:149], v[142:143], v[128:129] op_sel:[1,0,0] op_sel_hi:[1,1,1]
	ds_write_b32 v204, v196 offset:7888
	ds_write_b32 v206, v198 offset:7888
	v_mov_b32_dpp v194, v192 quad_perm:[1,0,3,2] row_mask:0xf bank_mask:0xf
	v_pk_fma_f32 v[122:123], v[192:193], v[136:137], v[122:123] op_sel_hi:[0,1,1]
	v_pk_fma_f32 v[126:127], v[194:195], v[136:137], v[126:127] op_sel_hi:[0,1,1]
	v_pk_fma_f32 v[124:125], v[192:193], v[138:139], v[124:125] op_sel_hi:[0,1,1]
	v_pk_fma_f32 v[128:129], v[194:195], v[138:139], v[128:129] op_sel_hi:[0,1,1]
	s_waitcnt lgkmcnt(7)
	v_pk_mul_f32 v[192:193], v[122:123], v[152:153]
	v_pk_mul_f32 v[194:195], v[126:127], v[152:153]
	v_pk_fma_f32 v[192:193], v[124:125], v[154:155], v[192:193]
	v_pk_fma_f32 v[194:195], v[128:129], v[154:155], v[194:195]
	v_add_f32_e32 v192, v192, v193
	v_add_f32_e32 v194, v194, v195
	v_pk_mul_f32 v[196:197], v[122:123], v[144:145]
	v_pk_mul_f32 v[198:199], v[126:127], v[144:145]
	v_pk_fma_f32 v[196:197], v[124:125], v[146:147], v[196:197]
	v_add_f32_dpp v192, v194, v192 quad_perm:[1,0,3,2] row_mask:0xf bank_mask:0xf
	v_pk_fma_f32 v[198:199], v[128:129], v[146:147], v[198:199]
	v_add_f32_e32 v196, v196, v197
	v_add_f32_dpp v192, v192, v192 quad_perm:[2,3,0,1] row_mask:0xf bank_mask:0xf
	v_add_f32_e32 v198, v198, v199
	s_waitcnt lgkmcnt(2)
	v_add_f32_dpp v192, v192, v192 row_ror:4 row_mask:0xf bank_mask:0xf
	v_pk_fma_f32 v[122:123], v[168:169], v[160:161], v[122:123] op_sel_hi:[0,1,1]
	v_pk_fma_f32 v[126:127], v[168:169], v[160:161], v[126:127] op_sel:[1,0,0] op_sel_hi:[1,1,1]
	v_pk_fma_f32 v[124:125], v[168:169], v[162:163], v[124:125] op_sel_hi:[0,1,1]
	v_add_f32_dpp v192, v192, v192 row_ror:8 row_mask:0xf bank_mask:0xf
	v_pk_fma_f32 v[128:129], v[168:169], v[162:163], v[128:129] op_sel:[1,0,0] op_sel_hi:[1,1,1]
	ds_write_b32 v204, v196 offset:8160
	ds_write_b32 v206, v198 offset:8160
	v_mov_b32_dpp v194, v192 quad_perm:[1,0,3,2] row_mask:0xf bank_mask:0xf
	v_pk_fma_f32 v[122:123], v[192:193], v[156:157], v[122:123] op_sel_hi:[0,1,1]
	v_pk_fma_f32 v[126:127], v[194:195], v[156:157], v[126:127] op_sel_hi:[0,1,1]
	v_pk_fma_f32 v[124:125], v[192:193], v[158:159], v[124:125] op_sel_hi:[0,1,1]
	v_pk_fma_f32 v[128:129], v[194:195], v[158:159], v[128:129] op_sel_hi:[0,1,1]
	v_add_u32_e32 v30, s0, v71
	ds_read_b128 v[200:203], v30
	v_pk_mul_f32 v[196:197], v[122:123], v[164:165]
	v_pk_mul_f32 v[198:199], v[126:127], v[164:165]
	v_pk_fma_f32 v[196:197], v[124:125], v[166:167], v[196:197]
	v_pk_fma_f32 v[198:199], v[128:129], v[166:167], v[198:199]
	v_add_f32_e32 v196, v196, v197
	v_add_f32_e32 v198, v198, v199
	ds_write_b32 v204, v196 offset:8432
	ds_write_b32 v206, v198 offset:8432
	s_waitcnt lgkmcnt(2)
	v_pk_mul_f32 v[122:123], v[122:123], v[200:201]
	v_pk_mul_f32 v[126:127], v[126:127], v[200:201]
	v_pk_mul_f32 v[124:125], v[124:125], v[202:203]
	v_pk_mul_f32 v[128:129], v[128:129], v[202:203]
